# kblocked_hbuf_fullline_dma_plus_p0_rewrite
# speedup vs baseline: 1.0762x; 1.0444x over previous
.LBB0_15:
	v_mov_b32_e32 v0, v181
	s_cmpk_gt_i32 s2, 0x255f
	v_mbcnt_lo_u32_b32 v183, -1, 0
	s_cbranch_scc1 .LBB0_44
	v_lshlrev_b32_e32 v1, 2, v0
	v_and_b32_e32 v12, 0xfc, v1
	v_max_i32_e32 v1, 0xf00, v0
	v_mov_b32_e32 v3, 0
	v_lshlrev_b32_e32 v2, 1, v12
	v_sub_u32_e32 v1, v1, v0
	v_lshl_add_u64 v[4:5], s[50:51], 0, v[2:3]
	v_lshlrev_b32_e32 v2, 2, v12
	v_add_u32_e32 v1, 0xff, v1
	s_waitcnt lgkmcnt(0)
	v_lshl_add_u64 v[10:11], s[62:63], 0, v[2:3]
	v_lshrrev_b32_e32 v2, 8, v1
	v_add_u32_e32 v13, 1, v2
	v_add_u32_e32 v2, -1, v2
	v_lshrrev_b32_e32 v14, 1, v2
	v_and_b32_e32 v6, 63, v0
	v_add_u32_e32 v14, 1, v14
	v_and_b32_e32 v15, 0x1fffffe, v13
	v_mbcnt_hi_u32_b32 v22, -1, v183
	s_movk_i32 s0, 0x1000
	v_lshlrev_b32_e32 v8, 2, v6
	s_movk_i32 s4, 0xff
	v_and_b32_e32 v19, 3, v14
	v_cmp_ne_u32_e64 s[10:11], v13, v15
	v_and_b32_e32 v13, 64, v22
	v_ashrrev_i32_e32 v7, 6, v0
	v_cmp_gt_i32_e64 s[0:1], s0, v0
	v_lshl_or_b32 v9, v6, 8, v8
	v_cmp_lt_u32_e64 s[4:5], s4, v1
	v_lshl_add_u32 v18, v15, 8, v0
	v_add_u32_e32 v1, 0x100, v0
	v_cmp_lt_u32_e64 s[6:7], 5, v2
	v_and_b32_e32 v20, -4, v14
	v_cmp_ne_u32_e64 s[8:9], 0, v19
	s_movk_i32 s62, 0xdfc0
	s_movk_i32 s63, 0x1010
	s_movk_i32 s68, 0x4040
	s_movk_i32 s69, 0x104
	s_movk_i32 s70, 0xeff
	s_mov_b32 s71, 0x10200000
	s_mov_b32 s72, 0x8000
	v_lshlrev_b32_e32 v12, 2, v12
	v_mov_b32_e32 v21, 0x358637bd
	s_mov_b32 s73, 0x800000
	v_lshlrev_b32_e32 v2, 1, v6
	v_add_u32_e32 v23, 64, v13
	v_xor_b32_e32 v24, 32, v22
	v_xor_b32_e32 v25, 16, v22
	v_xor_b32_e32 v26, 8, v22
	v_xor_b32_e32 v27, 4, v22
	v_xor_b32_e32 v28, 2, v22
	v_xor_b32_e32 v29, 1, v22
	s_mov_b32 s74, s2
	s_cmpk_lt_i32 s74, 0x2040
	s_cbranch_scc0 .Lrms_done
	v_and_b32_e32 v64, 63, v181
	v_lshrrev_b32_e32 v65, 6, v181
	v_lshlrev_b32_e32 v66, 4, v64
	v_lshlrev_b32_e32 v67, 3, v64
	v_lshrrev_b32_e32 v144, 3, v64
	s_mov_b32 s81, 0x204000
	v_mul_lo_u32 v144, v144, s81
	v_and_b32_e32 v145, 7, v64
	v_lshl_add_u32 v144, v145, 3, v144
	global_load_dwordx4 v[68:71], v[10:11], off
	global_load_dwordx4 v[72:75], v[10:11], off offset:1024
	global_load_dwordx4 v[76:79], v[10:11], off offset:2048
	global_load_dwordx4 v[80:83], v[10:11], off offset:3072
	s_cmpk_lt_u32 s74, 0x2000
	s_cselect_b32 s84, s52, s54
	s_cselect_b32 s85, s53, s55
	s_cselect_b32 s86, 0, 0x2000
	s_sub_u32 s86, s74, s86
	v_lshl_add_u32 v84, s86, 2, v65
	v_lshl_add_u32 v84, v84, 12, v66
	v_lshl_add_u32 v86, s74, 2, v65
	v_lshl_add_u32 v136, v86, 6, v144
	v_add_u32_e32 v137, 0x1020000, v136
	v_add_u32_e32 v138, 0x1020000, v137
	v_add_u32_e32 v139, 0x1020000, v138
	global_load_dwordx4 v[88:91], v84, s[84:85] nt
	global_load_dwordx4 v[92:95], v84, s[84:85] offset:1024 nt
	global_load_dwordx4 v[96:99], v84, s[84:85] offset:2048 nt
	global_load_dwordx4 v[100:103], v84, s[84:85] offset:3072 nt
	s_add_i32 s80, s74, s22
	s_cmpk_lt_i32 s80, 0x2040
	s_cbranch_scc0 .Lrms_last0
	s_cmpk_lt_u32 s80, 0x2000
	s_cselect_b32 s84, s52, s54
	s_cselect_b32 s85, s53, s55
	s_cselect_b32 s86, 0, 0x2000
	s_sub_u32 s86, s80, s86
	v_lshl_add_u32 v85, s86, 2, v65
	v_lshl_add_u32 v85, v85, 12, v66
	v_lshl_add_u32 v87, s80, 2, v65
	v_lshl_add_u32 v140, v87, 6, v144
	v_add_u32_e32 v141, 0x1020000, v140
	v_add_u32_e32 v142, 0x1020000, v141
	v_add_u32_e32 v143, 0x1020000, v142
	global_load_dwordx4 v[104:107], v85, s[84:85] nt
	global_load_dwordx4 v[108:111], v85, s[84:85] offset:1024 nt
	global_load_dwordx4 v[112:115], v85, s[84:85] offset:2048 nt
	global_load_dwordx4 v[116:119], v85, s[84:85] offset:3072 nt
	s_waitcnt vmcnt(4)
	v_mul_f32_e32 v120, v88, v88
	v_fmac_f32_e32 v120, v89, v89
	v_fmac_f32_e32 v120, v90, v90
	v_fmac_f32_e32 v120, v91, v91
	v_fmac_f32_e32 v120, v92, v92
	v_fmac_f32_e32 v120, v93, v93
	v_fmac_f32_e32 v120, v94, v94
	v_fmac_f32_e32 v120, v95, v95
	v_fmac_f32_e32 v120, v96, v96
	v_fmac_f32_e32 v120, v97, v97
	v_fmac_f32_e32 v120, v98, v98
	v_fmac_f32_e32 v120, v99, v99
	v_fmac_f32_e32 v120, v100, v100
	v_fmac_f32_e32 v120, v101, v101
	v_fmac_f32_e32 v120, v102, v102
	v_fmac_f32_e32 v120, v103, v103
	s_nop 1
	v_add_f32_dpp v120, v120, v120 quad_perm:[1,0,3,2] row_mask:0xf bank_mask:0xf
	s_nop 1
	v_add_f32_dpp v120, v120, v120 quad_perm:[2,3,0,1] row_mask:0xf bank_mask:0xf
	s_nop 1
	v_add_f32_dpp v120, v120, v120 row_half_mirror row_mask:0xf bank_mask:0xf
	s_nop 1
	v_add_f32_dpp v120, v120, v120 row_mirror row_mask:0xf bank_mask:0xf
	s_nop 1
	v_readlane_b32 s87, v120, 0
	v_readlane_b32 s88, v120, 16
	v_readlane_b32 s89, v120, 32
	v_readlane_b32 s90, v120, 48
	s_nop 1
	v_mov_b32_e32 v121, s87
	v_add_f32_e32 v121, s88, v121
	v_add_f32_e32 v121, s89, v121
	v_add_f32_e32 v121, s90, v121
	v_mov_b32_e32 v122, 0x358637bd
	v_fmamk_f32 v121, v121, 0x3a800000, v122
	v_rsq_f32_e32 v121, v121
	s_nop 0
	v_mul_f32_e32 v88, v88, v121
	v_mul_f32_e32 v89, v89, v121
	v_mul_f32_e32 v90, v90, v121
	v_mul_f32_e32 v91, v91, v121
	v_mul_f32_e32 v92, v92, v121
	v_mul_f32_e32 v93, v93, v121
	v_mul_f32_e32 v94, v94, v121
	v_mul_f32_e32 v95, v95, v121
	v_mul_f32_e32 v96, v96, v121
	v_mul_f32_e32 v97, v97, v121
	v_mul_f32_e32 v98, v98, v121
	v_mul_f32_e32 v99, v99, v121
	v_mul_f32_e32 v100, v100, v121
	v_mul_f32_e32 v101, v101, v121
	v_mul_f32_e32 v102, v102, v121
	v_mul_f32_e32 v103, v103, v121
	v_mul_f32_e32 v88, v68, v88
	v_mul_f32_e32 v89, v69, v89
	v_mul_f32_e32 v90, v70, v90
	v_mul_f32_e32 v91, v71, v91
	v_mul_f32_e32 v92, v72, v92
	v_mul_f32_e32 v93, v73, v93
	v_mul_f32_e32 v94, v74, v94
	v_mul_f32_e32 v95, v75, v95
	v_mul_f32_e32 v96, v76, v96
	v_mul_f32_e32 v97, v77, v97
	v_mul_f32_e32 v98, v78, v98
	v_mul_f32_e32 v99, v79, v99
	v_mul_f32_e32 v100, v80, v100
	v_mul_f32_e32 v101, v81, v101
	v_mul_f32_e32 v102, v82, v102
	v_mul_f32_e32 v103, v83, v103
	v_cvt_pk_bf16_f32 v124, v88, v89
	v_cvt_pk_bf16_f32 v125, v90, v91
	v_cvt_pk_bf16_f32 v126, v92, v93
	v_cvt_pk_bf16_f32 v127, v94, v95
	v_cvt_pk_bf16_f32 v128, v96, v97
	v_cvt_pk_bf16_f32 v129, v98, v99
	v_cvt_pk_bf16_f32 v130, v100, v101
	v_cvt_pk_bf16_f32 v131, v102, v103
	global_store_dwordx2 v136, v[124:125], s[50:51]
	global_store_dwordx2 v137, v[126:127], s[50:51]
	global_store_dwordx2 v138, v[128:129], s[50:51]
	global_store_dwordx2 v139, v[130:131], s[50:51]
	s_mov_b32 s74, s80
.Lrms_loop:
	s_add_i32 s80, s74, s22
	s_cmpk_lt_i32 s80, 0x2040
	s_cbranch_scc0 .Lrms_last1
	s_cmpk_lt_u32 s80, 0x2000
	s_cselect_b32 s84, s52, s54
	s_cselect_b32 s85, s53, s55
	s_cselect_b32 s86, 0, 0x2000
	s_sub_u32 s86, s80, s86
	v_lshl_add_u32 v84, s86, 2, v65
	v_lshl_add_u32 v84, v84, 12, v66
	v_lshl_add_u32 v86, s80, 2, v65
	v_lshl_add_u32 v136, v86, 6, v144
	v_add_u32_e32 v137, 0x1020000, v136
	v_add_u32_e32 v138, 0x1020000, v137
	v_add_u32_e32 v139, 0x1020000, v138
	global_load_dwordx4 v[88:91], v84, s[84:85] nt
	global_load_dwordx4 v[92:95], v84, s[84:85] offset:1024 nt
	global_load_dwordx4 v[96:99], v84, s[84:85] offset:2048 nt
	global_load_dwordx4 v[100:103], v84, s[84:85] offset:3072 nt
	s_waitcnt vmcnt(8)
	v_mul_f32_e32 v120, v104, v104
	v_fmac_f32_e32 v120, v105, v105
	v_fmac_f32_e32 v120, v106, v106
	v_fmac_f32_e32 v120, v107, v107
	v_fmac_f32_e32 v120, v108, v108
	v_fmac_f32_e32 v120, v109, v109
	v_fmac_f32_e32 v120, v110, v110
	v_fmac_f32_e32 v120, v111, v111
	v_fmac_f32_e32 v120, v112, v112
	v_fmac_f32_e32 v120, v113, v113
	v_fmac_f32_e32 v120, v114, v114
	v_fmac_f32_e32 v120, v115, v115
	v_fmac_f32_e32 v120, v116, v116
	v_fmac_f32_e32 v120, v117, v117
	v_fmac_f32_e32 v120, v118, v118
	v_fmac_f32_e32 v120, v119, v119
	s_nop 1
	v_add_f32_dpp v120, v120, v120 quad_perm:[1,0,3,2] row_mask:0xf bank_mask:0xf
	s_nop 1
	v_add_f32_dpp v120, v120, v120 quad_perm:[2,3,0,1] row_mask:0xf bank_mask:0xf
	s_nop 1
	v_add_f32_dpp v120, v120, v120 row_half_mirror row_mask:0xf bank_mask:0xf
	s_nop 1
	v_add_f32_dpp v120, v120, v120 row_mirror row_mask:0xf bank_mask:0xf
	s_nop 1
	v_readlane_b32 s87, v120, 0
	v_readlane_b32 s88, v120, 16
	v_readlane_b32 s89, v120, 32
	v_readlane_b32 s90, v120, 48
	s_nop 1
	v_mov_b32_e32 v121, s87
	v_add_f32_e32 v121, s88, v121
	v_add_f32_e32 v121, s89, v121
	v_add_f32_e32 v121, s90, v121
	v_mov_b32_e32 v122, 0x358637bd
	v_fmamk_f32 v121, v121, 0x3a800000, v122
	v_rsq_f32_e32 v121, v121
	s_nop 0
	v_mul_f32_e32 v104, v104, v121
	v_mul_f32_e32 v105, v105, v121
	v_mul_f32_e32 v106, v106, v121
	v_mul_f32_e32 v107, v107, v121
	v_mul_f32_e32 v108, v108, v121
	v_mul_f32_e32 v109, v109, v121
	v_mul_f32_e32 v110, v110, v121
	v_mul_f32_e32 v111, v111, v121
	v_mul_f32_e32 v112, v112, v121
	v_mul_f32_e32 v113, v113, v121
	v_mul_f32_e32 v114, v114, v121
	v_mul_f32_e32 v115, v115, v121
	v_mul_f32_e32 v116, v116, v121
	v_mul_f32_e32 v117, v117, v121
	v_mul_f32_e32 v118, v118, v121
	v_mul_f32_e32 v119, v119, v121
	v_mul_f32_e32 v104, v68, v104
	v_mul_f32_e32 v105, v69, v105
	v_mul_f32_e32 v106, v70, v106
	v_mul_f32_e32 v107, v71, v107
	v_mul_f32_e32 v108, v72, v108
	v_mul_f32_e32 v109, v73, v109
	v_mul_f32_e32 v110, v74, v110
	v_mul_f32_e32 v111, v75, v111
	v_mul_f32_e32 v112, v76, v112
	v_mul_f32_e32 v113, v77, v113
	v_mul_f32_e32 v114, v78, v114
	v_mul_f32_e32 v115, v79, v115
	v_mul_f32_e32 v116, v80, v116
	v_mul_f32_e32 v117, v81, v117
	v_mul_f32_e32 v118, v82, v118
	v_mul_f32_e32 v119, v83, v119
	v_cvt_pk_bf16_f32 v124, v104, v105
	v_cvt_pk_bf16_f32 v125, v106, v107
	v_cvt_pk_bf16_f32 v126, v108, v109
	v_cvt_pk_bf16_f32 v127, v110, v111
	v_cvt_pk_bf16_f32 v128, v112, v113
	v_cvt_pk_bf16_f32 v129, v114, v115
	v_cvt_pk_bf16_f32 v130, v116, v117
	v_cvt_pk_bf16_f32 v131, v118, v119
	global_store_dwordx2 v140, v[124:125], s[50:51]
	global_store_dwordx2 v141, v[126:127], s[50:51]
	global_store_dwordx2 v142, v[128:129], s[50:51]
	global_store_dwordx2 v143, v[130:131], s[50:51]
	s_mov_b32 s74, s80
	s_add_i32 s80, s74, s22
	s_cmpk_lt_i32 s80, 0x2040
	s_cbranch_scc0 .Lrms_last0
	s_cmpk_lt_u32 s80, 0x2000
	s_cselect_b32 s84, s52, s54
	s_cselect_b32 s85, s53, s55
	s_cselect_b32 s86, 0, 0x2000
	s_sub_u32 s86, s80, s86
	v_lshl_add_u32 v85, s86, 2, v65
	v_lshl_add_u32 v85, v85, 12, v66
	v_lshl_add_u32 v87, s80, 2, v65
	v_lshl_add_u32 v140, v87, 6, v144
	v_add_u32_e32 v141, 0x1020000, v140
	v_add_u32_e32 v142, 0x1020000, v141
	v_add_u32_e32 v143, 0x1020000, v142
	global_load_dwordx4 v[104:107], v85, s[84:85] nt
	global_load_dwordx4 v[108:111], v85, s[84:85] offset:1024 nt
	global_load_dwordx4 v[112:115], v85, s[84:85] offset:2048 nt
	global_load_dwordx4 v[116:119], v85, s[84:85] offset:3072 nt
	s_waitcnt vmcnt(8)
	v_mul_f32_e32 v120, v88, v88
	v_fmac_f32_e32 v120, v89, v89
	v_fmac_f32_e32 v120, v90, v90
	v_fmac_f32_e32 v120, v91, v91
	v_fmac_f32_e32 v120, v92, v92
	v_fmac_f32_e32 v120, v93, v93
	v_fmac_f32_e32 v120, v94, v94
	v_fmac_f32_e32 v120, v95, v95
	v_fmac_f32_e32 v120, v96, v96
	v_fmac_f32_e32 v120, v97, v97
	v_fmac_f32_e32 v120, v98, v98
	v_fmac_f32_e32 v120, v99, v99
	v_fmac_f32_e32 v120, v100, v100
	v_fmac_f32_e32 v120, v101, v101
	v_fmac_f32_e32 v120, v102, v102
	v_fmac_f32_e32 v120, v103, v103
	s_nop 1
	v_add_f32_dpp v120, v120, v120 quad_perm:[1,0,3,2] row_mask:0xf bank_mask:0xf
	s_nop 1
	v_add_f32_dpp v120, v120, v120 quad_perm:[2,3,0,1] row_mask:0xf bank_mask:0xf
	s_nop 1
	v_add_f32_dpp v120, v120, v120 row_half_mirror row_mask:0xf bank_mask:0xf
	s_nop 1
	v_add_f32_dpp v120, v120, v120 row_mirror row_mask:0xf bank_mask:0xf
	s_nop 1
	v_readlane_b32 s87, v120, 0
	v_readlane_b32 s88, v120, 16
	v_readlane_b32 s89, v120, 32
	v_readlane_b32 s90, v120, 48
	s_nop 1
	v_mov_b32_e32 v121, s87
	v_add_f32_e32 v121, s88, v121
	v_add_f32_e32 v121, s89, v121
	v_add_f32_e32 v121, s90, v121
	v_mov_b32_e32 v122, 0x358637bd
	v_fmamk_f32 v121, v121, 0x3a800000, v122
	v_rsq_f32_e32 v121, v121
	s_nop 0
	v_mul_f32_e32 v88, v88, v121
	v_mul_f32_e32 v89, v89, v121
	v_mul_f32_e32 v90, v90, v121
	v_mul_f32_e32 v91, v91, v121
	v_mul_f32_e32 v92, v92, v121
	v_mul_f32_e32 v93, v93, v121
	v_mul_f32_e32 v94, v94, v121
	v_mul_f32_e32 v95, v95, v121
	v_mul_f32_e32 v96, v96, v121
	v_mul_f32_e32 v97, v97, v121
	v_mul_f32_e32 v98, v98, v121
	v_mul_f32_e32 v99, v99, v121
	v_mul_f32_e32 v100, v100, v121
	v_mul_f32_e32 v101, v101, v121
	v_mul_f32_e32 v102, v102, v121
	v_mul_f32_e32 v103, v103, v121
	v_mul_f32_e32 v88, v68, v88
	v_mul_f32_e32 v89, v69, v89
	v_mul_f32_e32 v90, v70, v90
	v_mul_f32_e32 v91, v71, v91
	v_mul_f32_e32 v92, v72, v92
	v_mul_f32_e32 v93, v73, v93
	v_mul_f32_e32 v94, v74, v94
	v_mul_f32_e32 v95, v75, v95
	v_mul_f32_e32 v96, v76, v96
	v_mul_f32_e32 v97, v77, v97
	v_mul_f32_e32 v98, v78, v98
	v_mul_f32_e32 v99, v79, v99
	v_mul_f32_e32 v100, v80, v100
	v_mul_f32_e32 v101, v81, v101
	v_mul_f32_e32 v102, v82, v102
	v_mul_f32_e32 v103, v83, v103
	v_cvt_pk_bf16_f32 v124, v88, v89
	v_cvt_pk_bf16_f32 v125, v90, v91
	v_cvt_pk_bf16_f32 v126, v92, v93
	v_cvt_pk_bf16_f32 v127, v94, v95
	v_cvt_pk_bf16_f32 v128, v96, v97
	v_cvt_pk_bf16_f32 v129, v98, v99
	v_cvt_pk_bf16_f32 v130, v100, v101
	v_cvt_pk_bf16_f32 v131, v102, v103
	global_store_dwordx2 v136, v[124:125], s[50:51]
	global_store_dwordx2 v137, v[126:127], s[50:51]
	global_store_dwordx2 v138, v[128:129], s[50:51]
	global_store_dwordx2 v139, v[130:131], s[50:51]
	s_mov_b32 s74, s80
	s_branch .Lrms_loop
.Lrms_last0:
	s_waitcnt vmcnt(0)
	v_mul_f32_e32 v120, v88, v88
	v_fmac_f32_e32 v120, v89, v89
	v_fmac_f32_e32 v120, v90, v90
	v_fmac_f32_e32 v120, v91, v91
	v_fmac_f32_e32 v120, v92, v92
	v_fmac_f32_e32 v120, v93, v93
	v_fmac_f32_e32 v120, v94, v94
	v_fmac_f32_e32 v120, v95, v95
	v_fmac_f32_e32 v120, v96, v96
	v_fmac_f32_e32 v120, v97, v97
	v_fmac_f32_e32 v120, v98, v98
	v_fmac_f32_e32 v120, v99, v99
	v_fmac_f32_e32 v120, v100, v100
	v_fmac_f32_e32 v120, v101, v101
	v_fmac_f32_e32 v120, v102, v102
	v_fmac_f32_e32 v120, v103, v103
	s_nop 1
	v_add_f32_dpp v120, v120, v120 quad_perm:[1,0,3,2] row_mask:0xf bank_mask:0xf
	s_nop 1
	v_add_f32_dpp v120, v120, v120 quad_perm:[2,3,0,1] row_mask:0xf bank_mask:0xf
	s_nop 1
	v_add_f32_dpp v120, v120, v120 row_half_mirror row_mask:0xf bank_mask:0xf
	s_nop 1
	v_add_f32_dpp v120, v120, v120 row_mirror row_mask:0xf bank_mask:0xf
	s_nop 1
	v_readlane_b32 s87, v120, 0
	v_readlane_b32 s88, v120, 16
	v_readlane_b32 s89, v120, 32
	v_readlane_b32 s90, v120, 48
	s_nop 1
	v_mov_b32_e32 v121, s87
	v_add_f32_e32 v121, s88, v121
	v_add_f32_e32 v121, s89, v121
	v_add_f32_e32 v121, s90, v121
	v_mov_b32_e32 v122, 0x358637bd
	v_fmamk_f32 v121, v121, 0x3a800000, v122
	v_rsq_f32_e32 v121, v121
	s_nop 0
	v_mul_f32_e32 v88, v88, v121
	v_mul_f32_e32 v89, v89, v121
	v_mul_f32_e32 v90, v90, v121
	v_mul_f32_e32 v91, v91, v121
	v_mul_f32_e32 v92, v92, v121
	v_mul_f32_e32 v93, v93, v121
	v_mul_f32_e32 v94, v94, v121
	v_mul_f32_e32 v95, v95, v121
	v_mul_f32_e32 v96, v96, v121
	v_mul_f32_e32 v97, v97, v121
	v_mul_f32_e32 v98, v98, v121
	v_mul_f32_e32 v99, v99, v121
	v_mul_f32_e32 v100, v100, v121
	v_mul_f32_e32 v101, v101, v121
	v_mul_f32_e32 v102, v102, v121
	v_mul_f32_e32 v103, v103, v121
	v_mul_f32_e32 v88, v68, v88
	v_mul_f32_e32 v89, v69, v89
	v_mul_f32_e32 v90, v70, v90
	v_mul_f32_e32 v91, v71, v91
	v_mul_f32_e32 v92, v72, v92
	v_mul_f32_e32 v93, v73, v93
	v_mul_f32_e32 v94, v74, v94
	v_mul_f32_e32 v95, v75, v95
	v_mul_f32_e32 v96, v76, v96
	v_mul_f32_e32 v97, v77, v97
	v_mul_f32_e32 v98, v78, v98
	v_mul_f32_e32 v99, v79, v99
	v_mul_f32_e32 v100, v80, v100
	v_mul_f32_e32 v101, v81, v101
	v_mul_f32_e32 v102, v82, v102
	v_mul_f32_e32 v103, v83, v103
	v_cvt_pk_bf16_f32 v124, v88, v89
	v_cvt_pk_bf16_f32 v125, v90, v91
	v_cvt_pk_bf16_f32 v126, v92, v93
	v_cvt_pk_bf16_f32 v127, v94, v95
	v_cvt_pk_bf16_f32 v128, v96, v97
	v_cvt_pk_bf16_f32 v129, v98, v99
	v_cvt_pk_bf16_f32 v130, v100, v101
	v_cvt_pk_bf16_f32 v131, v102, v103
	global_store_dwordx2 v136, v[124:125], s[50:51]
	global_store_dwordx2 v137, v[126:127], s[50:51]
	global_store_dwordx2 v138, v[128:129], s[50:51]
	global_store_dwordx2 v139, v[130:131], s[50:51]
	s_mov_b32 s74, s80
	s_branch .Lrms_done
.Lrms_last1:
	s_waitcnt vmcnt(0)
	v_mul_f32_e32 v120, v104, v104
	v_fmac_f32_e32 v120, v105, v105
	v_fmac_f32_e32 v120, v106, v106
	v_fmac_f32_e32 v120, v107, v107
	v_fmac_f32_e32 v120, v108, v108
	v_fmac_f32_e32 v120, v109, v109
	v_fmac_f32_e32 v120, v110, v110
	v_fmac_f32_e32 v120, v111, v111
	v_fmac_f32_e32 v120, v112, v112
	v_fmac_f32_e32 v120, v113, v113
	v_fmac_f32_e32 v120, v114, v114
	v_fmac_f32_e32 v120, v115, v115
	v_fmac_f32_e32 v120, v116, v116
	v_fmac_f32_e32 v120, v117, v117
	v_fmac_f32_e32 v120, v118, v118
	v_fmac_f32_e32 v120, v119, v119
	s_nop 1
	v_add_f32_dpp v120, v120, v120 quad_perm:[1,0,3,2] row_mask:0xf bank_mask:0xf
	s_nop 1
	v_add_f32_dpp v120, v120, v120 quad_perm:[2,3,0,1] row_mask:0xf bank_mask:0xf
	s_nop 1
	v_add_f32_dpp v120, v120, v120 row_half_mirror row_mask:0xf bank_mask:0xf
	s_nop 1
	v_add_f32_dpp v120, v120, v120 row_mirror row_mask:0xf bank_mask:0xf
	s_nop 1
	v_readlane_b32 s87, v120, 0
	v_readlane_b32 s88, v120, 16
	v_readlane_b32 s89, v120, 32
	v_readlane_b32 s90, v120, 48
	s_nop 1
	v_mov_b32_e32 v121, s87
	v_add_f32_e32 v121, s88, v121
	v_add_f32_e32 v121, s89, v121
	v_add_f32_e32 v121, s90, v121
	v_mov_b32_e32 v122, 0x358637bd
	v_fmamk_f32 v121, v121, 0x3a800000, v122
	v_rsq_f32_e32 v121, v121
	s_nop 0
	v_mul_f32_e32 v104, v104, v121
	v_mul_f32_e32 v105, v105, v121
	v_mul_f32_e32 v106, v106, v121
	v_mul_f32_e32 v107, v107, v121
	v_mul_f32_e32 v108, v108, v121
	v_mul_f32_e32 v109, v109, v121
	v_mul_f32_e32 v110, v110, v121
	v_mul_f32_e32 v111, v111, v121
	v_mul_f32_e32 v112, v112, v121
	v_mul_f32_e32 v113, v113, v121
	v_mul_f32_e32 v114, v114, v121
	v_mul_f32_e32 v115, v115, v121
	v_mul_f32_e32 v116, v116, v121
	v_mul_f32_e32 v117, v117, v121
	v_mul_f32_e32 v118, v118, v121
	v_mul_f32_e32 v119, v119, v121
	v_mul_f32_e32 v104, v68, v104
	v_mul_f32_e32 v105, v69, v105
	v_mul_f32_e32 v106, v70, v106
	v_mul_f32_e32 v107, v71, v107
	v_mul_f32_e32 v108, v72, v108
	v_mul_f32_e32 v109, v73, v109
	v_mul_f32_e32 v110, v74, v110
	v_mul_f32_e32 v111, v75, v111
	v_mul_f32_e32 v112, v76, v112
	v_mul_f32_e32 v113, v77, v113
	v_mul_f32_e32 v114, v78, v114
	v_mul_f32_e32 v115, v79, v115
	v_mul_f32_e32 v116, v80, v116
	v_mul_f32_e32 v117, v81, v117
	v_mul_f32_e32 v118, v82, v118
	v_mul_f32_e32 v119, v83, v119
	v_cvt_pk_bf16_f32 v124, v104, v105
	v_cvt_pk_bf16_f32 v125, v106, v107
	v_cvt_pk_bf16_f32 v126, v108, v109
	v_cvt_pk_bf16_f32 v127, v110, v111
	v_cvt_pk_bf16_f32 v128, v112, v113
	v_cvt_pk_bf16_f32 v129, v114, v115
	v_cvt_pk_bf16_f32 v130, v116, v117
	v_cvt_pk_bf16_f32 v131, v118, v119
	global_store_dwordx2 v140, v[124:125], s[50:51]
	global_store_dwordx2 v141, v[126:127], s[50:51]
	global_store_dwordx2 v142, v[128:129], s[50:51]
	global_store_dwordx2 v143, v[130:131], s[50:51]
	s_mov_b32 s74, s80

.LBB0_95:
	s_or_b64 exec, exec, s[0:1]
	s_and_b32 s28, s2, 7
	s_xor_b32 s0, s28, 7
	s_add_i32 s0, s22, s0
	s_ashr_i32 s1, s0, 31
	s_lshr_b32 s1, s1, 29
	s_add_i32 s0, s0, s1
	s_lshr_b32 s88, s2, 3
	s_ashr_i32 s89, s0, 3
	s_cmp_lt_i32 s22, 8
	s_cselect_b64 s[0:1], -1, 0
	v_writelane_b32 v244, s0, 2
	s_barrier
	s_nop 0
	v_writelane_b32 v244, s1, 3
	s_and_b64 s[0:1], s[0:1], exec
	s_cselect_b32 s78, s2, s28
	s_cselect_b32 s29, 0, s88
	s_cmp_gt_i32 s78, 63
	s_cselect_b64 s[0:1], -1, 0
	s_cmp_gt_u32 s29, 63
	s_cselect_b64 s[4:5], -1, 0
	s_or_b64 s[0:1], s[0:1], s[4:5]
	s_and_b64 vcc, exec, s[0:1]
	s_cbranch_vccnz .LBB0_251
	v_readlane_b32 s0, v244, 2
	s_min_i32 s79, s22, 8
	v_readlane_b32 s1, v244, 3
	s_and_b64 s[0:1], s[0:1], exec
	s_cselect_b32 s80, 1, s89
	s_add_u32 s4, s20, 0x10200000
	s_addc_u32 s5, s21, 0
	s_mov_b64 s[0:1], 0
	v_mov_b32_e32 v129, 0
	s_mov_b64 s[6:7], 0x20000
	s_mov_b64 s[8:9], 0x2000
	s_mov_b64 s[10:11], 0x3000
	s_mov_b64 s[12:13], 0x204000
	s_mov_b64 s[14:15], 0x1000
	s_mov_b64 s[16:17], 0x60040
	s_mov_b64 s[34:35], 0x10200040
	s_mov_b64 s[46:47], 0x10220040
	s_movk_i32 s81, 0x80
	s_movk_i32 s82, 0x7fff
	s_movk_i32 s83, 0x1800
	s_mov_b64 s[62:63], 0x8292000
	s_movk_i32 s84, 0x1fff
	s_movk_i32 s85, 0x1ffc
	s_mov_b64 s[64:65], 0x8100000
	s_movk_i32 s86, 0x110
	v_mov_b32_e32 v140, 0x70
	s_mov_b32 s87, s29
	s_branch .LBB0_98

.LBB0_98:
	s_lshl_b32 s24, s78, 1
	s_and_b32 s24, s24, -8
	s_and_b32 s33, s87, 7
	s_or_b32 s69, s24, s33
	s_lshl_b32 s24, s78, 3
	s_and_b32 s72, s24, 24
	s_ashr_i32 s24, s87, 3
	s_add_i32 s72, s72, s24
	v_mov_b32_e32 v141, v181
	v_mov_b32_e32 v2, v181
	s_lshl_b32 s68, s72, 7
	s_lshl_b32 s90, s69, 8
	v_ashrrev_i32_e32 v142, 2, v2
	v_lshlrev_b32_e32 v3, 3, v2
	v_add_u32_e32 v0, s68, v142
	v_bitop3_b32 v4, v3, 24, v2 bitop3:0x48
	v_ashrrev_i32_e32 v1, 31, v0
	v_lshlrev_b32_e32 v144, 4, v2
	v_lshlrev_b64 v[0:1], 11, v[0:1]
	s_and_b64 vcc, exec, s[0:1]
	v_add_u32_e32 v143, 0x1000, v144
	v_add_u32_e32 v139, 0x2000, v144
	v_add_u32_e32 v138, 0x3000, v144
	v_add_u32_e32 v137, 0x4000, v144
	v_add_u32_e32 v136, 0x5000, v144
	v_lshlrev_b32_e32 v130, 1, v4
	s_cbranch_vccnz .LBB0_100
	v_add_u32_e32 v4, s90, v142
	v_ashrrev_i32_e32 v5, 31, v4
	v_lshlrev_b64 v[4:5], 6, v[4:5]
	v_lshl_add_u64 v[4:5], s[50:51], 0, v[4:5]
	v_mov_b32_e32 v131, v129
	v_readfirstlane_b32 s0, v144
	v_lshl_add_u64 v[4:5], v[4:5], 0, v[130:131]
	s_mov_b32 m0, s0
	v_readfirstlane_b32 s0, v143
	s_barrier
	global_load_lds_dwordx4 v[4:5], off
	v_lshl_add_u64 v[8:9], v[4:5], 0, s[14:15]
	s_mov_b32 m0, s0
	v_readfirstlane_b32 s0, v139
	global_load_lds_dwordx4 v[8:9], off
	v_lshl_add_u64 v[8:9], v[4:5], 0, s[8:9]
	s_mov_b32 m0, s0
	v_readfirstlane_b32 s0, v138
	v_lshl_add_u64 v[6:7], s[4:5], 0, v[0:1]
	global_load_lds_dwordx4 v[8:9], off
	v_lshl_add_u64 v[4:5], v[4:5], 0, s[10:11]
	s_mov_b32 m0, s0
	v_readfirstlane_b32 s0, v137
	v_lshl_add_u64 v[6:7], v[6:7], 0, v[130:131]
	global_load_lds_dwordx4 v[4:5], off
	s_mov_b32 m0, s0
	v_readfirstlane_b32 s0, v136
	global_load_lds_dwordx4 v[6:7], off
	v_lshl_add_u64 v[4:5], v[6:7], 0, s[6:7]
	s_mov_b32 m0, s0
	s_nop 0
	global_load_lds_dwordx4 v[4:5], off
.LBB0_100:
	s_lshl_b32 s0, s78, 9
	s_and_b32 s0, s0, 0xfffff800
	s_lshl_b32 s1, s33, 8
	v_xor_b32_e32 v4, v3, v2
	v_lshlrev_b32_e32 v2, 6, v2
	s_or_b32 s0, s1, s0
	v_and_b32_e32 v131, 48, v4
	v_and_b32_e32 v147, 0x1000, v2
	v_and_b32_e32 v145, 0x3c0, v2
	v_and_b32_e32 v146, 0xffffe000, v2
	v_add_u32_e32 v2, s0, v142
	v_lshlrev_b32_e32 v4, 1, v4
	v_ashrrev_i32_e32 v3, 31, v2
	v_and_b32_e32 v128, 48, v4
	v_lshlrev_b64 v[2:3], 6, v[2:3]
	v_lshl_add_u64 v[0:1], v[0:1], 0, v[128:129]
	v_or_b32_e32 v2, v2, v128
	v_lshl_add_u64 v[134:135], s[20:21], 0, v[0:1]
	v_mov_b32_e32 v0, 0
	s_mov_b32 s70, 1
	v_lshl_add_u64 v[132:133], s[50:51], 0, v[2:3]
	s_mov_b64 s[0:1], 0
	v_mov_b32_e32 v1, v0
	v_mov_b32_e32 v2, v0
	v_mov_b32_e32 v3, v0
	v_mov_b32_e32 v4, v0
	v_mov_b32_e32 v5, v0
	v_mov_b32_e32 v6, v0
	v_mov_b32_e32 v7, v0
	v_mov_b32_e32 v8, v0
	v_mov_b32_e32 v9, v0
	v_mov_b32_e32 v10, v0
	v_mov_b32_e32 v11, v0
	v_mov_b32_e32 v12, v0
	v_mov_b32_e32 v13, v0
	v_mov_b32_e32 v14, v0
	v_mov_b32_e32 v15, v0
	v_mov_b32_e32 v16, v0
	v_mov_b32_e32 v17, v0
	v_mov_b32_e32 v18, v0
	v_mov_b32_e32 v19, v0
	v_mov_b32_e32 v20, v0
	v_mov_b32_e32 v21, v0
	v_mov_b32_e32 v22, v0
	v_mov_b32_e32 v23, v0
	v_mov_b32_e32 v24, v0
	v_mov_b32_e32 v25, v0
	v_mov_b32_e32 v26, v0
	v_mov_b32_e32 v27, v0
	v_mov_b32_e32 v28, v0
	v_mov_b32_e32 v29, v0
	v_mov_b32_e32 v30, v0
	v_mov_b32_e32 v31, v0
	v_mov_b32_e32 v32, v0
	v_mov_b32_e32 v33, v0
	v_mov_b32_e32 v34, v0
	v_mov_b32_e32 v35, v0
	v_mov_b32_e32 v36, v0
	v_mov_b32_e32 v37, v0
	v_mov_b32_e32 v38, v0
	v_mov_b32_e32 v39, v0
	v_mov_b32_e32 v40, v0
	v_mov_b32_e32 v41, v0
	v_mov_b32_e32 v42, v0
	v_mov_b32_e32 v43, v0
	v_mov_b32_e32 v44, v0
	v_mov_b32_e32 v45, v0
	v_mov_b32_e32 v46, v0
	v_mov_b32_e32 v47, v0
	v_mov_b32_e32 v48, v0
	v_mov_b32_e32 v49, v0
	v_mov_b32_e32 v50, v0
	v_mov_b32_e32 v51, v0
	v_mov_b32_e32 v52, v0
	v_mov_b32_e32 v53, v0
	v_mov_b32_e32 v54, v0
	v_mov_b32_e32 v55, v0
	v_mov_b32_e32 v56, v0
	v_mov_b32_e32 v57, v0
	v_mov_b32_e32 v58, v0
	v_mov_b32_e32 v59, v0
	v_mov_b32_e32 v64, v0
	v_mov_b32_e32 v65, v0
	v_mov_b32_e32 v66, v0
	v_mov_b32_e32 v67, v0
	v_mov_b32_e32 v60, v0
	v_mov_b32_e32 v61, v0
	v_mov_b32_e32 v62, v0
	v_mov_b32_e32 v63, v0
	v_mov_b32_e32 v68, v0
	v_mov_b32_e32 v69, v0
	v_mov_b32_e32 v70, v0
	v_mov_b32_e32 v71, v0
	v_mov_b32_e32 v72, v0
	v_mov_b32_e32 v73, v0
	v_mov_b32_e32 v74, v0
	v_mov_b32_e32 v75, v0
	v_mov_b32_e32 v76, v0
	v_mov_b32_e32 v77, v0
	v_mov_b32_e32 v78, v0
	v_mov_b32_e32 v79, v0
	v_mov_b32_e32 v80, v0
	v_mov_b32_e32 v81, v0
	v_mov_b32_e32 v82, v0
	v_mov_b32_e32 v83, v0
	v_mov_b32_e32 v84, v0
	v_mov_b32_e32 v85, v0
	v_mov_b32_e32 v86, v0
	v_mov_b32_e32 v87, v0
	v_mov_b32_e32 v88, v0
	v_mov_b32_e32 v89, v0
	v_mov_b32_e32 v90, v0
	v_mov_b32_e32 v91, v0
	v_mov_b32_e32 v92, v0
	v_mov_b32_e32 v93, v0
	v_mov_b32_e32 v94, v0
	v_mov_b32_e32 v95, v0
	v_mov_b32_e32 v96, v0
	v_mov_b32_e32 v97, v0
	v_mov_b32_e32 v98, v0
	v_mov_b32_e32 v99, v0
	v_mov_b32_e32 v100, v0
	v_mov_b32_e32 v101, v0
	v_mov_b32_e32 v102, v0
	v_mov_b32_e32 v103, v0
	v_mov_b32_e32 v104, v0
	v_mov_b32_e32 v105, v0
	v_mov_b32_e32 v106, v0
	v_mov_b32_e32 v107, v0
	v_mov_b32_e32 v108, v0
	v_mov_b32_e32 v109, v0
	v_mov_b32_e32 v110, v0
	v_mov_b32_e32 v111, v0
	v_mov_b32_e32 v112, v0
	v_mov_b32_e32 v113, v0
	v_mov_b32_e32 v114, v0
	v_mov_b32_e32 v115, v0
	v_mov_b32_e32 v116, v0
	v_mov_b32_e32 v117, v0
	v_mov_b32_e32 v118, v0
	v_mov_b32_e32 v119, v0
	v_mov_b32_e32 v120, v0
	v_mov_b32_e32 v121, v0
	v_mov_b32_e32 v122, v0
	v_mov_b32_e32 v123, v0
	v_mov_b32_e32 v124, v0
	v_mov_b32_e32 v125, v0
	v_mov_b32_e32 v126, v0
	v_mov_b32_e32 v127, v0
	v_lshl_add_u64 v[226:227], v[132:133], 0, s[12:13]
	v_lshl_add_u64 v[228:229], v[226:227], 0, s[14:15]
	v_lshl_add_u64 v[230:231], v[228:229], 0, s[14:15]
	v_lshl_add_u64 v[232:233], v[230:231], 0, s[14:15]
	v_lshl_add_u64 v[234:235], v[134:135], 0, s[34:35]
	v_lshl_add_u64 v[236:237], v[134:135], 0, s[46:47]
	v_add3_u32 v216, v146, v145, v131
	v_add3_u32 v217, v147, v145, v131
	v_readfirstlane_b32 s30, v144
	s_nop 3
	s_add_u32 s24, s30, 0x6000
	s_mov_b32 m0, s24
	s_nop 0
	global_load_lds_dwordx4 v[226:227], off
	v_lshl_add_u64 v[226:227], v[226:227], 0, s[12:13]
	s_nop 0
	s_add_u32 s97, s24, 0x1000
	s_mov_b32 m0, s97
	s_nop 0
	global_load_lds_dwordx4 v[228:229], off
	v_lshl_add_u64 v[228:229], v[228:229], 0, s[12:13]
	s_nop 0
	s_add_u32 s97, s24, 0x2000
	s_mov_b32 m0, s97
	s_nop 0
	global_load_lds_dwordx4 v[230:231], off
	v_lshl_add_u64 v[230:231], v[230:231], 0, s[12:13]
	s_nop 0
	s_add_u32 s97, s24, 0x3000
	s_mov_b32 m0, s97
	s_nop 0
	global_load_lds_dwordx4 v[232:233], off
	v_lshl_add_u64 v[232:233], v[232:233], 0, s[12:13]
	s_nop 0
	s_add_u32 s97, s24, 0x4000
	s_mov_b32 m0, s97
	s_nop 0
	global_load_lds_dwordx4 v[234:235], off
	v_lshl_add_u64 v[234:235], v[234:235], 0, 64
	s_nop 0
	s_add_u32 s97, s24, 0x5000
	s_mov_b32 m0, s97
	s_nop 0
	global_load_lds_dwordx4 v[236:237], off
	v_lshl_add_u64 v[236:237], v[236:237], 0, 64
	s_nop 0
	s_add_u32 s24, s30, 0xc000
	s_mov_b32 m0, s24
	s_nop 0
	global_load_lds_dwordx4 v[226:227], off
	v_lshl_add_u64 v[226:227], v[226:227], 0, s[12:13]
	s_nop 0
	s_add_u32 s97, s24, 0x1000
	s_mov_b32 m0, s97
	s_nop 0
	global_load_lds_dwordx4 v[228:229], off
	v_lshl_add_u64 v[228:229], v[228:229], 0, s[12:13]
	s_nop 0
	s_add_u32 s97, s24, 0x2000
	s_mov_b32 m0, s97
	s_nop 0
	global_load_lds_dwordx4 v[230:231], off
	v_lshl_add_u64 v[230:231], v[230:231], 0, s[12:13]
	s_nop 0
	s_add_u32 s97, s24, 0x3000
	s_mov_b32 m0, s97
	s_nop 0
	global_load_lds_dwordx4 v[232:233], off
	v_lshl_add_u64 v[232:233], v[232:233], 0, s[12:13]
	s_nop 0
	s_add_u32 s97, s24, 0x4000
	s_mov_b32 m0, s97
	s_nop 0
	global_load_lds_dwordx4 v[234:235], off
	v_lshl_add_u64 v[234:235], v[234:235], 0, 64
	s_nop 0
	s_add_u32 s97, s24, 0x5000
	s_mov_b32 m0, s97
	s_nop 0
	global_load_lds_dwordx4 v[236:237], off
	v_lshl_add_u64 v[236:237], v[236:237], 0, 64
	s_nop 0
	s_waitcnt vmcnt(12) lgkmcnt(0)
	s_barrier
	ds_read_b128 v[148:151], v217 offset:16384
	ds_read_b128 v[152:155], v217 offset:17408
	ds_read_b128 v[156:159], v217 offset:18432
	ds_read_b128 v[160:163], v217 offset:19456
	ds_read_b128 v[164:167], v216 offset:0
	ds_read_b128 v[168:171], v216 offset:1024
	ds_read_b128 v[172:175], v216 offset:2048
	ds_read_b128 v[176:179], v216 offset:3072
	s_mov_b32 s18, 0
	s_movk_i32 s25, 0x6000
	s_mov_b32 s32, 0xc000
	s_mov_b32 s70, 0
.Lg1_loop:
	v_add_u32_e32 v218, s18, v216
	ds_read_b128 v[184:187], v218 offset:4096
	ds_read_b128 v[188:191], v218 offset:5120
	ds_read_b128 v[192:195], v218 offset:6144
	ds_read_b128 v[196:199], v218 offset:7168
	v_add_u32_e32 v219, s25, v216
	v_add_u32_e32 v220, s25, v217
	s_waitcnt lgkmcnt(7)
	v_mfma_f32_16x16x32_bf16 v[124:127], v[148:151], v[164:167], v[124:127]
	v_mfma_f32_16x16x32_bf16 v[120:123], v[152:155], v[164:167], v[120:123]
	v_mfma_f32_16x16x32_bf16 v[116:119], v[156:159], v[164:167], v[116:119]
	v_mfma_f32_16x16x32_bf16 v[112:115], v[160:163], v[164:167], v[112:115]
	s_waitcnt lgkmcnt(6)
	v_mfma_f32_16x16x32_bf16 v[108:111], v[148:151], v[168:171], v[108:111]
	v_mfma_f32_16x16x32_bf16 v[104:107], v[152:155], v[168:171], v[104:107]
	v_mfma_f32_16x16x32_bf16 v[100:103], v[156:159], v[168:171], v[100:103]
	v_mfma_f32_16x16x32_bf16 v[96:99], v[160:163], v[168:171], v[96:99]
	s_waitcnt lgkmcnt(5)
	v_mfma_f32_16x16x32_bf16 v[92:95], v[148:151], v[172:175], v[92:95]
	v_mfma_f32_16x16x32_bf16 v[88:91], v[152:155], v[172:175], v[88:91]
	v_mfma_f32_16x16x32_bf16 v[84:87], v[156:159], v[172:175], v[84:87]
	v_mfma_f32_16x16x32_bf16 v[80:83], v[160:163], v[172:175], v[80:83]
	s_waitcnt lgkmcnt(4)
	v_mfma_f32_16x16x32_bf16 v[76:79], v[148:151], v[176:179], v[76:79]
	v_mfma_f32_16x16x32_bf16 v[72:75], v[152:155], v[176:179], v[72:75]
	v_mfma_f32_16x16x32_bf16 v[68:71], v[156:159], v[176:179], v[68:71]
	v_mfma_f32_16x16x32_bf16 v[60:63], v[160:163], v[176:179], v[60:63]
	s_waitcnt vmcnt(6) lgkmcnt(0)
	s_barrier
	v_mfma_f32_16x16x32_bf16 v[64:67], v[148:151], v[184:187], v[64:67]
	s_add_u32 s24, s18, s30
	s_mov_b32 m0, s24
	ds_read_b128 v[200:203], v220 offset:16384
	v_mfma_f32_16x16x32_bf16 v[56:59], v[152:155], v[184:187], v[56:59]
	global_load_lds_dwordx4 v[226:227], off
	v_lshl_add_u64 v[226:227], v[226:227], 0, s[12:13]
	ds_read_b128 v[204:207], v220 offset:17408
	v_mfma_f32_16x16x32_bf16 v[52:55], v[156:159], v[184:187], v[52:55]
	s_add_u32 s97, s24, 0x1000
	s_mov_b32 m0, s97
	ds_read_b128 v[208:211], v220 offset:18432
	v_mfma_f32_16x16x32_bf16 v[48:51], v[160:163], v[184:187], v[48:51]
	global_load_lds_dwordx4 v[228:229], off
	v_lshl_add_u64 v[228:229], v[228:229], 0, s[12:13]
	ds_read_b128 v[212:215], v220 offset:19456
	v_mfma_f32_16x16x32_bf16 v[44:47], v[148:151], v[188:191], v[44:47]
	s_add_u32 s97, s24, 0x2000
	s_mov_b32 m0, s97
	ds_read_b128 v[164:167], v219 offset:0
	v_mfma_f32_16x16x32_bf16 v[40:43], v[152:155], v[188:191], v[40:43]
	global_load_lds_dwordx4 v[230:231], off
	v_lshl_add_u64 v[230:231], v[230:231], 0, s[12:13]
	ds_read_b128 v[168:171], v219 offset:1024
	v_mfma_f32_16x16x32_bf16 v[36:39], v[156:159], v[188:191], v[36:39]
	s_add_u32 s97, s24, 0x3000
	s_mov_b32 m0, s97
	ds_read_b128 v[172:175], v219 offset:2048
	v_mfma_f32_16x16x32_bf16 v[32:35], v[160:163], v[188:191], v[32:35]
	global_load_lds_dwordx4 v[232:233], off
	v_lshl_add_u64 v[232:233], v[232:233], 0, s[12:13]
	ds_read_b128 v[176:179], v219 offset:3072
	v_mfma_f32_16x16x32_bf16 v[28:31], v[148:151], v[192:195], v[28:31]
	s_add_u32 s97, s24, 0x4000
	s_mov_b32 m0, s97
	v_mfma_f32_16x16x32_bf16 v[24:27], v[152:155], v[192:195], v[24:27]
	global_load_lds_dwordx4 v[234:235], off
	v_lshl_add_u64 v[234:235], v[234:235], 0, 64
	v_mfma_f32_16x16x32_bf16 v[20:23], v[156:159], v[192:195], v[20:23]
	s_add_u32 s97, s24, 0x5000
	s_mov_b32 m0, s97
	v_mfma_f32_16x16x32_bf16 v[16:19], v[160:163], v[192:195], v[16:19]
	global_load_lds_dwordx4 v[236:237], off
	v_lshl_add_u64 v[236:237], v[236:237], 0, 64
	v_mfma_f32_16x16x32_bf16 v[12:15], v[148:151], v[196:199], v[12:15]
	v_mfma_f32_16x16x32_bf16 v[8:11], v[152:155], v[196:199], v[8:11]
	v_mfma_f32_16x16x32_bf16 v[4:7], v[156:159], v[196:199], v[4:7]
	v_mfma_f32_16x16x32_bf16 v[0:3], v[160:163], v[196:199], v[0:3]
	s_mov_b32 s24, s18
	s_mov_b32 s18, s25
	s_mov_b32 s25, s32
	s_mov_b32 s32, s24
	v_add_u32_e32 v218, s18, v216
	ds_read_b128 v[184:187], v218 offset:4096
	ds_read_b128 v[188:191], v218 offset:5120
	ds_read_b128 v[192:195], v218 offset:6144
	ds_read_b128 v[196:199], v218 offset:7168
	v_add_u32_e32 v219, s25, v216
	v_add_u32_e32 v220, s25, v217
	s_waitcnt lgkmcnt(7)
	v_mfma_f32_16x16x32_bf16 v[124:127], v[200:203], v[164:167], v[124:127]
	v_mfma_f32_16x16x32_bf16 v[120:123], v[204:207], v[164:167], v[120:123]
	v_mfma_f32_16x16x32_bf16 v[116:119], v[208:211], v[164:167], v[116:119]
	v_mfma_f32_16x16x32_bf16 v[112:115], v[212:215], v[164:167], v[112:115]
	s_waitcnt lgkmcnt(6)
	v_mfma_f32_16x16x32_bf16 v[108:111], v[200:203], v[168:171], v[108:111]
	v_mfma_f32_16x16x32_bf16 v[104:107], v[204:207], v[168:171], v[104:107]
	v_mfma_f32_16x16x32_bf16 v[100:103], v[208:211], v[168:171], v[100:103]
	v_mfma_f32_16x16x32_bf16 v[96:99], v[212:215], v[168:171], v[96:99]
	s_waitcnt lgkmcnt(5)
	v_mfma_f32_16x16x32_bf16 v[92:95], v[200:203], v[172:175], v[92:95]
	v_mfma_f32_16x16x32_bf16 v[88:91], v[204:207], v[172:175], v[88:91]
	v_mfma_f32_16x16x32_bf16 v[84:87], v[208:211], v[172:175], v[84:87]
	v_mfma_f32_16x16x32_bf16 v[80:83], v[212:215], v[172:175], v[80:83]
	s_waitcnt lgkmcnt(4)
	v_mfma_f32_16x16x32_bf16 v[76:79], v[200:203], v[176:179], v[76:79]
	v_mfma_f32_16x16x32_bf16 v[72:75], v[204:207], v[176:179], v[72:75]
	v_mfma_f32_16x16x32_bf16 v[68:71], v[208:211], v[176:179], v[68:71]
	v_mfma_f32_16x16x32_bf16 v[60:63], v[212:215], v[176:179], v[60:63]
	s_waitcnt vmcnt(6) lgkmcnt(0)
	s_barrier
	v_mfma_f32_16x16x32_bf16 v[64:67], v[200:203], v[184:187], v[64:67]
	s_add_u32 s24, s18, s30
	s_mov_b32 m0, s24
	ds_read_b128 v[148:151], v220 offset:16384
	v_mfma_f32_16x16x32_bf16 v[56:59], v[204:207], v[184:187], v[56:59]
	global_load_lds_dwordx4 v[226:227], off
	v_lshl_add_u64 v[226:227], v[226:227], 0, s[12:13]
	ds_read_b128 v[152:155], v220 offset:17408
	v_mfma_f32_16x16x32_bf16 v[52:55], v[208:211], v[184:187], v[52:55]
	s_add_u32 s97, s24, 0x1000
	s_mov_b32 m0, s97
	ds_read_b128 v[156:159], v220 offset:18432
	v_mfma_f32_16x16x32_bf16 v[48:51], v[212:215], v[184:187], v[48:51]
	global_load_lds_dwordx4 v[228:229], off
	v_lshl_add_u64 v[228:229], v[228:229], 0, s[12:13]
	ds_read_b128 v[160:163], v220 offset:19456
	v_mfma_f32_16x16x32_bf16 v[44:47], v[200:203], v[188:191], v[44:47]
	s_add_u32 s97, s24, 0x2000
	s_mov_b32 m0, s97
	ds_read_b128 v[164:167], v219 offset:0
	v_mfma_f32_16x16x32_bf16 v[40:43], v[204:207], v[188:191], v[40:43]
	global_load_lds_dwordx4 v[230:231], off
	v_lshl_add_u64 v[230:231], v[230:231], 0, s[12:13]
	ds_read_b128 v[168:171], v219 offset:1024
	v_mfma_f32_16x16x32_bf16 v[36:39], v[208:211], v[188:191], v[36:39]
	s_add_u32 s97, s24, 0x3000
	s_mov_b32 m0, s97
	ds_read_b128 v[172:175], v219 offset:2048
	v_mfma_f32_16x16x32_bf16 v[32:35], v[212:215], v[188:191], v[32:35]
	global_load_lds_dwordx4 v[232:233], off
	v_lshl_add_u64 v[232:233], v[232:233], 0, s[12:13]
	ds_read_b128 v[176:179], v219 offset:3072
	v_mfma_f32_16x16x32_bf16 v[28:31], v[200:203], v[192:195], v[28:31]
	s_add_u32 s97, s24, 0x4000
	s_mov_b32 m0, s97
	v_mfma_f32_16x16x32_bf16 v[24:27], v[204:207], v[192:195], v[24:27]
	global_load_lds_dwordx4 v[234:235], off
	v_lshl_add_u64 v[234:235], v[234:235], 0, 64
	v_mfma_f32_16x16x32_bf16 v[20:23], v[208:211], v[192:195], v[20:23]
	s_add_u32 s97, s24, 0x5000
	s_mov_b32 m0, s97
	v_mfma_f32_16x16x32_bf16 v[16:19], v[212:215], v[192:195], v[16:19]
	global_load_lds_dwordx4 v[236:237], off
	v_lshl_add_u64 v[236:237], v[236:237], 0, 64
	v_mfma_f32_16x16x32_bf16 v[12:15], v[200:203], v[196:199], v[12:15]
	v_mfma_f32_16x16x32_bf16 v[8:11], v[204:207], v[196:199], v[8:11]
	v_mfma_f32_16x16x32_bf16 v[4:7], v[208:211], v[196:199], v[4:7]
	v_mfma_f32_16x16x32_bf16 v[0:3], v[212:215], v[196:199], v[0:3]
	s_mov_b32 s24, s18
	s_mov_b32 s18, s25
	s_mov_b32 s25, s32
	s_mov_b32 s32, s24
	s_add_i32 s70, s70, 1
	s_cmp_lt_u32 s70, 14
	s_cbranch_scc1 .Lg1_loop
	v_add_u32_e32 v218, s18, v216
	ds_read_b128 v[184:187], v218 offset:4096
	ds_read_b128 v[188:191], v218 offset:5120
	ds_read_b128 v[192:195], v218 offset:6144
	ds_read_b128 v[196:199], v218 offset:7168
	v_add_u32_e32 v219, s25, v216
	v_add_u32_e32 v220, s25, v217
	s_waitcnt lgkmcnt(7)
	v_mfma_f32_16x16x32_bf16 v[124:127], v[148:151], v[164:167], v[124:127]
	v_mfma_f32_16x16x32_bf16 v[120:123], v[152:155], v[164:167], v[120:123]
	v_mfma_f32_16x16x32_bf16 v[116:119], v[156:159], v[164:167], v[116:119]
	v_mfma_f32_16x16x32_bf16 v[112:115], v[160:163], v[164:167], v[112:115]
	s_waitcnt lgkmcnt(6)
	v_mfma_f32_16x16x32_bf16 v[108:111], v[148:151], v[168:171], v[108:111]
	v_mfma_f32_16x16x32_bf16 v[104:107], v[152:155], v[168:171], v[104:107]
	v_mfma_f32_16x16x32_bf16 v[100:103], v[156:159], v[168:171], v[100:103]
	v_mfma_f32_16x16x32_bf16 v[96:99], v[160:163], v[168:171], v[96:99]
	s_waitcnt lgkmcnt(5)
	v_mfma_f32_16x16x32_bf16 v[92:95], v[148:151], v[172:175], v[92:95]
	v_mfma_f32_16x16x32_bf16 v[88:91], v[152:155], v[172:175], v[88:91]
	v_mfma_f32_16x16x32_bf16 v[84:87], v[156:159], v[172:175], v[84:87]
	v_mfma_f32_16x16x32_bf16 v[80:83], v[160:163], v[172:175], v[80:83]
	s_waitcnt lgkmcnt(4)
	v_mfma_f32_16x16x32_bf16 v[76:79], v[148:151], v[176:179], v[76:79]
	v_mfma_f32_16x16x32_bf16 v[72:75], v[152:155], v[176:179], v[72:75]
	v_mfma_f32_16x16x32_bf16 v[68:71], v[156:159], v[176:179], v[68:71]
	v_mfma_f32_16x16x32_bf16 v[60:63], v[160:163], v[176:179], v[60:63]
	s_waitcnt vmcnt(6) lgkmcnt(0)
	s_barrier
	v_mfma_f32_16x16x32_bf16 v[64:67], v[148:151], v[184:187], v[64:67]
	s_add_u32 s24, s18, s30
	s_mov_b32 m0, s24
	ds_read_b128 v[200:203], v220 offset:16384
	v_mfma_f32_16x16x32_bf16 v[56:59], v[152:155], v[184:187], v[56:59]
	global_load_lds_dwordx4 v[226:227], off
	v_lshl_add_u64 v[226:227], v[226:227], 0, s[12:13]
	ds_read_b128 v[204:207], v220 offset:17408
	v_mfma_f32_16x16x32_bf16 v[52:55], v[156:159], v[184:187], v[52:55]
	s_add_u32 s97, s24, 0x1000
	s_mov_b32 m0, s97
	ds_read_b128 v[208:211], v220 offset:18432
	v_mfma_f32_16x16x32_bf16 v[48:51], v[160:163], v[184:187], v[48:51]
	global_load_lds_dwordx4 v[228:229], off
	v_lshl_add_u64 v[228:229], v[228:229], 0, s[12:13]
	ds_read_b128 v[212:215], v220 offset:19456
	v_mfma_f32_16x16x32_bf16 v[44:47], v[148:151], v[188:191], v[44:47]
	s_add_u32 s97, s24, 0x2000
	s_mov_b32 m0, s97
	ds_read_b128 v[164:167], v219 offset:0
	v_mfma_f32_16x16x32_bf16 v[40:43], v[152:155], v[188:191], v[40:43]
	global_load_lds_dwordx4 v[230:231], off
	v_lshl_add_u64 v[230:231], v[230:231], 0, s[12:13]
	ds_read_b128 v[168:171], v219 offset:1024
	v_mfma_f32_16x16x32_bf16 v[36:39], v[156:159], v[188:191], v[36:39]
	s_add_u32 s97, s24, 0x3000
	s_mov_b32 m0, s97
	ds_read_b128 v[172:175], v219 offset:2048
	v_mfma_f32_16x16x32_bf16 v[32:35], v[160:163], v[188:191], v[32:35]
	global_load_lds_dwordx4 v[232:233], off
	v_lshl_add_u64 v[232:233], v[232:233], 0, s[12:13]
	ds_read_b128 v[176:179], v219 offset:3072
	v_mfma_f32_16x16x32_bf16 v[28:31], v[148:151], v[192:195], v[28:31]
	s_add_u32 s97, s24, 0x4000
	s_mov_b32 m0, s97
	v_mfma_f32_16x16x32_bf16 v[24:27], v[152:155], v[192:195], v[24:27]
	global_load_lds_dwordx4 v[234:235], off
	v_lshl_add_u64 v[234:235], v[234:235], 0, 64
	v_mfma_f32_16x16x32_bf16 v[20:23], v[156:159], v[192:195], v[20:23]
	s_add_u32 s97, s24, 0x5000
	s_mov_b32 m0, s97
	v_mfma_f32_16x16x32_bf16 v[16:19], v[160:163], v[192:195], v[16:19]
	global_load_lds_dwordx4 v[236:237], off
	v_lshl_add_u64 v[236:237], v[236:237], 0, 64
	v_mfma_f32_16x16x32_bf16 v[12:15], v[148:151], v[196:199], v[12:15]
	v_mfma_f32_16x16x32_bf16 v[8:11], v[152:155], v[196:199], v[8:11]
	v_mfma_f32_16x16x32_bf16 v[4:7], v[156:159], v[196:199], v[4:7]
	v_mfma_f32_16x16x32_bf16 v[0:3], v[160:163], v[196:199], v[0:3]
	s_mov_b32 s24, s18
	s_mov_b32 s18, s25
	s_mov_b32 s25, s32
	s_mov_b32 s32, s24
	v_add_u32_e32 v218, s18, v216
	ds_read_b128 v[184:187], v218 offset:4096
	ds_read_b128 v[188:191], v218 offset:5120
	ds_read_b128 v[192:195], v218 offset:6144
	ds_read_b128 v[196:199], v218 offset:7168
	v_add_u32_e32 v219, s25, v216
	v_add_u32_e32 v220, s25, v217
	s_waitcnt lgkmcnt(7)
	v_mfma_f32_16x16x32_bf16 v[124:127], v[200:203], v[164:167], v[124:127]
	v_mfma_f32_16x16x32_bf16 v[120:123], v[204:207], v[164:167], v[120:123]
	v_mfma_f32_16x16x32_bf16 v[116:119], v[208:211], v[164:167], v[116:119]
	v_mfma_f32_16x16x32_bf16 v[112:115], v[212:215], v[164:167], v[112:115]
	s_waitcnt lgkmcnt(6)
	v_mfma_f32_16x16x32_bf16 v[108:111], v[200:203], v[168:171], v[108:111]
	v_mfma_f32_16x16x32_bf16 v[104:107], v[204:207], v[168:171], v[104:107]
	v_mfma_f32_16x16x32_bf16 v[100:103], v[208:211], v[168:171], v[100:103]
	v_mfma_f32_16x16x32_bf16 v[96:99], v[212:215], v[168:171], v[96:99]
	s_waitcnt lgkmcnt(5)
	v_mfma_f32_16x16x32_bf16 v[92:95], v[200:203], v[172:175], v[92:95]
	v_mfma_f32_16x16x32_bf16 v[88:91], v[204:207], v[172:175], v[88:91]
	v_mfma_f32_16x16x32_bf16 v[84:87], v[208:211], v[172:175], v[84:87]
	v_mfma_f32_16x16x32_bf16 v[80:83], v[212:215], v[172:175], v[80:83]
	s_waitcnt lgkmcnt(4)
	v_mfma_f32_16x16x32_bf16 v[76:79], v[200:203], v[176:179], v[76:79]
	v_mfma_f32_16x16x32_bf16 v[72:75], v[204:207], v[176:179], v[72:75]
	v_mfma_f32_16x16x32_bf16 v[68:71], v[208:211], v[176:179], v[68:71]
	v_mfma_f32_16x16x32_bf16 v[60:63], v[212:215], v[176:179], v[60:63]
	s_waitcnt vmcnt(6) lgkmcnt(0)
	s_barrier
	v_mfma_f32_16x16x32_bf16 v[64:67], v[200:203], v[184:187], v[64:67]
	ds_read_b128 v[148:151], v220 offset:16384
	v_mfma_f32_16x16x32_bf16 v[56:59], v[204:207], v[184:187], v[56:59]
	ds_read_b128 v[152:155], v220 offset:17408
	v_mfma_f32_16x16x32_bf16 v[52:55], v[208:211], v[184:187], v[52:55]
	ds_read_b128 v[156:159], v220 offset:18432
	v_mfma_f32_16x16x32_bf16 v[48:51], v[212:215], v[184:187], v[48:51]
	ds_read_b128 v[160:163], v220 offset:19456
	v_mfma_f32_16x16x32_bf16 v[44:47], v[200:203], v[188:191], v[44:47]
	ds_read_b128 v[164:167], v219 offset:0
	v_mfma_f32_16x16x32_bf16 v[40:43], v[204:207], v[188:191], v[40:43]
	ds_read_b128 v[168:171], v219 offset:1024
	v_mfma_f32_16x16x32_bf16 v[36:39], v[208:211], v[188:191], v[36:39]
	ds_read_b128 v[172:175], v219 offset:2048
	v_mfma_f32_16x16x32_bf16 v[32:35], v[212:215], v[188:191], v[32:35]
	ds_read_b128 v[176:179], v219 offset:3072
	v_mfma_f32_16x16x32_bf16 v[28:31], v[200:203], v[192:195], v[28:31]
	v_mfma_f32_16x16x32_bf16 v[24:27], v[204:207], v[192:195], v[24:27]
	v_mfma_f32_16x16x32_bf16 v[20:23], v[208:211], v[192:195], v[20:23]
	v_mfma_f32_16x16x32_bf16 v[16:19], v[212:215], v[192:195], v[16:19]
	v_mfma_f32_16x16x32_bf16 v[12:15], v[200:203], v[196:199], v[12:15]
	v_mfma_f32_16x16x32_bf16 v[8:11], v[204:207], v[196:199], v[8:11]
	v_mfma_f32_16x16x32_bf16 v[4:7], v[208:211], v[196:199], v[4:7]
	v_mfma_f32_16x16x32_bf16 v[0:3], v[212:215], v[196:199], v[0:3]
	s_mov_b32 s24, s18
	s_mov_b32 s18, s25
	s_mov_b32 s25, s32
	s_mov_b32 s32, s24
	v_add_u32_e32 v218, s18, v216
	ds_read_b128 v[184:187], v218 offset:4096
	ds_read_b128 v[188:191], v218 offset:5120
	ds_read_b128 v[192:195], v218 offset:6144
	ds_read_b128 v[196:199], v218 offset:7168
	v_add_u32_e32 v219, s25, v216
	v_add_u32_e32 v220, s25, v217
	s_waitcnt lgkmcnt(7)
	v_mfma_f32_16x16x32_bf16 v[124:127], v[148:151], v[164:167], v[124:127]
	v_mfma_f32_16x16x32_bf16 v[120:123], v[152:155], v[164:167], v[120:123]
	v_mfma_f32_16x16x32_bf16 v[116:119], v[156:159], v[164:167], v[116:119]
	v_mfma_f32_16x16x32_bf16 v[112:115], v[160:163], v[164:167], v[112:115]
	s_waitcnt lgkmcnt(6)
	v_mfma_f32_16x16x32_bf16 v[108:111], v[148:151], v[168:171], v[108:111]
	v_mfma_f32_16x16x32_bf16 v[104:107], v[152:155], v[168:171], v[104:107]
	v_mfma_f32_16x16x32_bf16 v[100:103], v[156:159], v[168:171], v[100:103]
	v_mfma_f32_16x16x32_bf16 v[96:99], v[160:163], v[168:171], v[96:99]
	s_waitcnt lgkmcnt(5)
	v_mfma_f32_16x16x32_bf16 v[92:95], v[148:151], v[172:175], v[92:95]
	v_mfma_f32_16x16x32_bf16 v[88:91], v[152:155], v[172:175], v[88:91]
	v_mfma_f32_16x16x32_bf16 v[84:87], v[156:159], v[172:175], v[84:87]
	v_mfma_f32_16x16x32_bf16 v[80:83], v[160:163], v[172:175], v[80:83]
	s_waitcnt lgkmcnt(4)
	v_mfma_f32_16x16x32_bf16 v[76:79], v[148:151], v[176:179], v[76:79]
	v_mfma_f32_16x16x32_bf16 v[72:75], v[152:155], v[176:179], v[72:75]
	v_mfma_f32_16x16x32_bf16 v[68:71], v[156:159], v[176:179], v[68:71]
	v_mfma_f32_16x16x32_bf16 v[60:63], v[160:163], v[176:179], v[60:63]
	s_waitcnt vmcnt(0) lgkmcnt(0)
	s_barrier
	v_mfma_f32_16x16x32_bf16 v[64:67], v[148:151], v[184:187], v[64:67]
	ds_read_b128 v[200:203], v220 offset:16384
	v_mfma_f32_16x16x32_bf16 v[56:59], v[152:155], v[184:187], v[56:59]
	ds_read_b128 v[204:207], v220 offset:17408
	v_mfma_f32_16x16x32_bf16 v[52:55], v[156:159], v[184:187], v[52:55]
	ds_read_b128 v[208:211], v220 offset:18432
	v_mfma_f32_16x16x32_bf16 v[48:51], v[160:163], v[184:187], v[48:51]
	ds_read_b128 v[212:215], v220 offset:19456
	v_mfma_f32_16x16x32_bf16 v[44:47], v[148:151], v[188:191], v[44:47]
	ds_read_b128 v[164:167], v219 offset:0
	v_mfma_f32_16x16x32_bf16 v[40:43], v[152:155], v[188:191], v[40:43]
	ds_read_b128 v[168:171], v219 offset:1024
	v_mfma_f32_16x16x32_bf16 v[36:39], v[156:159], v[188:191], v[36:39]
	ds_read_b128 v[172:175], v219 offset:2048
	v_mfma_f32_16x16x32_bf16 v[32:35], v[160:163], v[188:191], v[32:35]
	ds_read_b128 v[176:179], v219 offset:3072
	v_mfma_f32_16x16x32_bf16 v[28:31], v[148:151], v[192:195], v[28:31]
	v_mfma_f32_16x16x32_bf16 v[24:27], v[152:155], v[192:195], v[24:27]
	v_mfma_f32_16x16x32_bf16 v[20:23], v[156:159], v[192:195], v[20:23]
	v_mfma_f32_16x16x32_bf16 v[16:19], v[160:163], v[192:195], v[16:19]
	v_mfma_f32_16x16x32_bf16 v[12:15], v[148:151], v[196:199], v[12:15]
	v_mfma_f32_16x16x32_bf16 v[8:11], v[152:155], v[196:199], v[8:11]
	v_mfma_f32_16x16x32_bf16 v[4:7], v[156:159], v[196:199], v[4:7]
	v_mfma_f32_16x16x32_bf16 v[0:3], v[160:163], v[196:199], v[0:3]
	s_mov_b32 s24, s18
	s_mov_b32 s18, s25
	s_mov_b32 s25, s32
	s_mov_b32 s32, s24
	v_add_u32_e32 v218, s18, v216
	ds_read_b128 v[184:187], v218 offset:4096
	ds_read_b128 v[188:191], v218 offset:5120
	ds_read_b128 v[192:195], v218 offset:6144
	ds_read_b128 v[196:199], v218 offset:7168
	s_waitcnt lgkmcnt(7)
	v_mfma_f32_16x16x32_bf16 v[124:127], v[200:203], v[164:167], v[124:127]
	v_mfma_f32_16x16x32_bf16 v[120:123], v[204:207], v[164:167], v[120:123]
	v_mfma_f32_16x16x32_bf16 v[116:119], v[208:211], v[164:167], v[116:119]
	v_mfma_f32_16x16x32_bf16 v[112:115], v[212:215], v[164:167], v[112:115]
	s_waitcnt lgkmcnt(6)
	v_mfma_f32_16x16x32_bf16 v[108:111], v[200:203], v[168:171], v[108:111]
	v_mfma_f32_16x16x32_bf16 v[104:107], v[204:207], v[168:171], v[104:107]
	v_mfma_f32_16x16x32_bf16 v[100:103], v[208:211], v[168:171], v[100:103]
	v_mfma_f32_16x16x32_bf16 v[96:99], v[212:215], v[168:171], v[96:99]
	s_waitcnt lgkmcnt(5)
	v_mfma_f32_16x16x32_bf16 v[92:95], v[200:203], v[172:175], v[92:95]
	v_mfma_f32_16x16x32_bf16 v[88:91], v[204:207], v[172:175], v[88:91]
	v_mfma_f32_16x16x32_bf16 v[84:87], v[208:211], v[172:175], v[84:87]
	v_mfma_f32_16x16x32_bf16 v[80:83], v[212:215], v[172:175], v[80:83]
	s_waitcnt lgkmcnt(4)
	v_mfma_f32_16x16x32_bf16 v[76:79], v[200:203], v[176:179], v[76:79]
	v_mfma_f32_16x16x32_bf16 v[72:75], v[204:207], v[176:179], v[72:75]
	v_mfma_f32_16x16x32_bf16 v[68:71], v[208:211], v[176:179], v[68:71]
	v_mfma_f32_16x16x32_bf16 v[60:63], v[212:215], v[176:179], v[60:63]
	s_waitcnt lgkmcnt(0)
	s_barrier
	v_mfma_f32_16x16x32_bf16 v[64:67], v[200:203], v[184:187], v[64:67]
	v_mfma_f32_16x16x32_bf16 v[56:59], v[204:207], v[184:187], v[56:59]
	v_mfma_f32_16x16x32_bf16 v[52:55], v[208:211], v[184:187], v[52:55]
	v_mfma_f32_16x16x32_bf16 v[48:51], v[212:215], v[184:187], v[48:51]
	v_mfma_f32_16x16x32_bf16 v[44:47], v[200:203], v[188:191], v[44:47]
	v_mfma_f32_16x16x32_bf16 v[40:43], v[204:207], v[188:191], v[40:43]
	v_mfma_f32_16x16x32_bf16 v[36:39], v[208:211], v[188:191], v[36:39]
	v_mfma_f32_16x16x32_bf16 v[32:35], v[212:215], v[188:191], v[32:35]
	v_mfma_f32_16x16x32_bf16 v[28:31], v[200:203], v[192:195], v[28:31]
	v_mfma_f32_16x16x32_bf16 v[24:27], v[204:207], v[192:195], v[24:27]
	v_mfma_f32_16x16x32_bf16 v[20:23], v[208:211], v[192:195], v[20:23]
	v_mfma_f32_16x16x32_bf16 v[16:19], v[212:215], v[192:195], v[16:19]
	v_mfma_f32_16x16x32_bf16 v[12:15], v[200:203], v[196:199], v[12:15]
	v_mfma_f32_16x16x32_bf16 v[8:11], v[204:207], v[196:199], v[8:11]
	v_mfma_f32_16x16x32_bf16 v[4:7], v[208:211], v[196:199], v[4:7]
	v_mfma_f32_16x16x32_bf16 v[0:3], v[212:215], v[196:199], v[0:3]
	s_mov_b32 s24, s18
	s_mov_b32 s18, s25
	s_mov_b32 s25, s32
	s_mov_b32 s32, s24
	s_add_i32 s0, s87, s80
	s_cmp_gt_i32 s0, 63
	s_cselect_b32 s1, s79, 0
	s_cselect_b32 s87, s29, s0
	s_add_i32 s78, s1, s78
	s_max_i32 s0, s87, s78
	s_cmp_gt_i32 s0, 63
	s_cselect_b64 s[70:71], -1, 0
	s_cmp_lt_i32 s0, 64
	s_cbranch_scc0 .LBB0_104
	s_lshl_b32 s0, s78, 1
	s_and_b32 s0, s0, 0xfffff8
	s_and_b32 s1, s87, 7
	s_or_b32 s0, s0, s1
	s_lshl_b32 s1, s78, 3
	s_and_b32 s1, s1, 24
	s_lshr_b32 s24, s87, 3
	s_add_i32 s1, s1, s24
	v_lshl_add_u32 v132, s0, 8, v142
	v_ashrrev_i32_e32 v133, 31, v132
	v_lshl_add_u32 v134, s1, 7, v142
	v_lshlrev_b64 v[132:133], 6, v[132:133]
	v_ashrrev_i32_e32 v135, 31, v134
	v_lshl_add_u64 v[132:133], s[50:51], 0, v[132:133]
	v_mov_b32_e32 v131, v129
	v_lshlrev_b64 v[134:135], 11, v[134:135]
	v_readfirstlane_b32 s0, v144
	v_lshl_add_u64 v[132:133], v[132:133], 0, v[130:131]
	v_lshl_add_u64 v[134:135], s[4:5], 0, v[134:135]
	s_mov_b32 m0, s0
	v_readfirstlane_b32 s0, v143
	v_lshl_add_u64 v[130:131], v[134:135], 0, v[130:131]
	global_load_lds_dwordx4 v[132:133], off
	v_lshl_add_u64 v[134:135], v[132:133], 0, s[14:15]
	s_mov_b32 m0, s0
	v_readfirstlane_b32 s0, v139
	global_load_lds_dwordx4 v[134:135], off
	v_lshl_add_u64 v[134:135], v[132:133], 0, s[8:9]
	s_mov_b32 m0, s0
	v_readfirstlane_b32 s0, v138
	global_load_lds_dwordx4 v[134:135], off
	v_lshl_add_u64 v[132:133], v[132:133], 0, s[10:11]
	s_mov_b32 m0, s0
	v_readfirstlane_b32 s0, v137
	global_load_lds_dwordx4 v[132:133], off
	s_mov_b32 m0, s0
	v_readfirstlane_b32 s0, v136
	global_load_lds_dwordx4 v[130:131], off
	v_lshl_add_u64 v[130:131], v[130:131], 0, s[6:7]
	s_mov_b32 m0, s0
	s_nop 0
	global_load_lds_dwordx4 v[130:131], off

.LBB0_251:
	s_cmpk_gt_i32 s2, 0xa0
	v_writelane_b32 v244, s94, 4
	s_nop 1
	v_writelane_b32 v244, s95, 5
	s_cbranch_scc1 .LBB0_411
	s_add_u32 s4, s20, 0x10200000
	s_addc_u32 s5, s21, 0
	s_add_u32 s6, s20, 0x10c40000
	s_addc_u32 s7, s21, 0
	s_lshl_b32 s0, s2, 8
	s_add_i32 s29, s0, 0xffffe000
	s_lshl_b32 s84, s22, 8
	s_lshl_b32 s85, s2, 7
	s_lshl_b32 s86, s22, 7
	v_mov_b32_e32 v129, 0
	s_mov_b64 s[8:9], 0x20000
	s_mov_b64 s[98:99], 0x1000
	s_mov_b64 s[10:11], 0x200000
	s_mov_b64 s[12:13], 0x201000
	s_mov_b64 s[14:15], 0x202000
	s_mov_b64 s[16:17], 0x203000
	s_mov_b64 s[34:35], 0x404000
	s_mov_b64 s[46:47], 0x405000
	s_mov_b64 s[62:63], 0x406000
	s_mov_b64 s[64:65], 0x407000
	s_mov_b64 s[68:69], 0x10200040
	s_mov_b64 s[70:71], 0x10220040
	s_movk_i32 s87, 0x7fff
	s_movk_i32 s90, 0x1800
	s_mov_b64 s[72:73], 0x8292000
	s_movk_i32 s91, 0x1fff
	s_movk_i32 s92, 0x1ffc
	s_mov_b64 s[74:75], 0x8100000
	s_movk_i32 s93, 0x80
	s_movk_i32 s94, 0x110
	s_brev_b32 s95, 8
	v_mov_b32_e32 v140, 0x70
	s_mov_b32 s96, s2
	s_branch .LBB0_255

.LBB0_255:
	s_cmp_gt_i32 s96, 31
	s_mov_b64 s[0:1], -1
	s_cbranch_scc0 .LBB0_261
	v_mov_b32_e32 v36, v181
	v_mov_b32_e32 v12, v181
	s_lshl_b32 s33, s96, 8
	v_lshlrev_b32_e32 v13, 3, v12
	v_ashrrev_i32_e32 v0, 2, v12
	v_bitop3_b32 v1, v13, 24, v12 bitop3:0x48
	s_addk_i32 s33, 0xe000
	v_lshlrev_b32_e32 v128, 1, v1
	v_ashrrev_i32_e32 v1, 31, v0
	v_add_u32_e32 v2, s33, v0
	v_lshlrev_b64 v[4:5], 11, v[0:1]
	v_ashrrev_i32_e32 v3, 31, v2
	v_lshl_add_u64 v[6:7], s[4:5], 0, v[4:5]
	v_lshlrev_b64 v[2:3], 6, v[2:3]
	v_lshl_add_u64 v[6:7], v[6:7], 0, v[128:129]
	s_mov_b64 s[0:1], 0x800000
	v_lshlrev_b32_e32 v37, 4, v12
	v_lshl_add_u64 v[2:3], s[50:51], 0, v[2:3]
	v_lshl_add_u64 v[8:9], v[6:7], 0, s[0:1]
	v_readfirstlane_b32 s0, v37
	v_add_u32_e32 v1, 0x1000, v37
	v_lshl_add_u64 v[2:3], v[2:3], 0, v[128:129]
	s_mov_b32 m0, s0
	v_readfirstlane_b32 s0, v1
	s_waitcnt vmcnt(0)
	s_barrier
	global_load_lds_dwordx4 v[2:3], off
	v_lshl_add_u64 v[10:11], v[2:3], 0, s[98:99]
	s_mov_b32 m0, s0
	s_mov_b64 s[0:1], 0x2000
	v_add_u32_e32 v1, 0x2000, v37
	global_load_lds_dwordx4 v[10:11], off
	v_lshl_add_u64 v[10:11], v[2:3], 0, s[0:1]
	v_readfirstlane_b32 s0, v1
	s_mov_b32 m0, s0
	s_mov_b64 s[0:1], 0x3000
	v_add_u32_e32 v1, 0x3000, v37
	v_lshl_add_u64 v[2:3], v[2:3], 0, s[0:1]
	v_readfirstlane_b32 s0, v1
	v_add_u32_e32 v1, 0x4000, v37
	global_load_lds_dwordx4 v[10:11], off
	s_mov_b32 m0, s0
	v_readfirstlane_b32 s0, v1
	global_load_lds_dwordx4 v[2:3], off
	s_mov_b32 m0, s0
	s_mov_b64 s[0:1], 0x820000
	v_add_u32_e32 v1, 0x5000, v37
	v_lshl_add_u64 v[2:3], v[6:7], 0, s[0:1]
	v_readfirstlane_b32 s0, v1
	global_load_lds_dwordx4 v[8:9], off
	s_mov_b32 m0, s0
	v_lshlrev_b32_e32 v1, 6, v12
	global_load_lds_dwordx4 v[2:3], off
	v_xor_b32_e32 v2, v13, v12
	v_add_u32_e32 v0, s29, v0
	v_and_b32_e32 v40, 0x1000, v1
	v_and_b32_e32 v39, 0x3c0, v1
	v_and_b32_e32 v41, 0xffffe000, v1
	v_ashrrev_i32_e32 v1, 31, v0
	v_lshlrev_b32_e32 v2, 1, v2
	v_lshlrev_b64 v[0:1], 6, v[0:1]
	v_and_b32_e32 v2, 48, v2
	v_or_b32_e32 v0, v0, v2
	v_lshl_add_u64 v[32:33], s[50:51], 0, v[0:1]
	v_or_b32_e32 v4, v4, v2
	v_mov_b32_e32 v0, 0
	s_mov_b32 s76, 1
	v_bitop3_b32 v38, v13, 48, v12 bitop3:0x48
	v_lshl_add_u64 v[34:35], s[20:21], 0, v[4:5]
	s_mov_b64 s[0:1], 0
	s_mov_b64 s[100:101], 0
	v_mov_b32_e32 v1, v0
	v_mov_b32_e32 v2, v0
	v_mov_b32_e32 v3, v0
	v_mov_b32_e32 v4, v0
	v_mov_b32_e32 v5, v0
	v_mov_b32_e32 v6, v0
	v_mov_b32_e32 v7, v0
	v_mov_b32_e32 v8, v0
	v_mov_b32_e32 v9, v0
	v_mov_b32_e32 v10, v0
	v_mov_b32_e32 v11, v0
	v_mov_b32_e32 v12, v0
	v_mov_b32_e32 v13, v0
	v_mov_b32_e32 v14, v0
	v_mov_b32_e32 v15, v0
	v_mov_b32_e32 v16, v0
	v_mov_b32_e32 v17, v0
	v_mov_b32_e32 v18, v0
	v_mov_b32_e32 v19, v0
	v_mov_b32_e32 v20, v0
	v_mov_b32_e32 v21, v0
	v_mov_b32_e32 v22, v0
	v_mov_b32_e32 v23, v0
	v_mov_b32_e32 v24, v0
	v_mov_b32_e32 v25, v0
	v_mov_b32_e32 v26, v0
	v_mov_b32_e32 v27, v0
	v_mov_b32_e32 v28, v0
	v_mov_b32_e32 v29, v0
	v_mov_b32_e32 v30, v0
	v_mov_b32_e32 v31, v0
	s_waitcnt vmcnt(0) lgkmcnt(0)
	s_barrier
.LBB0_257:
	s_bitcmp1_b32 s76, 0
	s_cselect_b32 s24, 0x6000, 0
	v_add_u32_e32 v46, s24, v37
	v_lshl_add_u64 v[42:43], v[32:33], 0, s[100:101]
	v_readfirstlane_b32 s24, v46
	s_nop 0
	s_mov_b32 m0, s24
	s_mov_b64 s[24:25], 0x204000
	v_lshl_add_u64 v[44:45], v[42:43], 0, s[24:25]
	s_mov_b64 s[24:25], 0x205000
	v_add_u32_e32 v47, 0x1000, v46
	global_load_lds_dwordx4 v[44:45], off
	v_lshl_add_u64 v[44:45], v[42:43], 0, s[24:25]
	v_readfirstlane_b32 s24, v47
	s_mov_b32 m0, s24
	s_mov_b64 s[24:25], 0x206000
	v_add_u32_e32 v47, 0x2000, v46
	global_load_lds_dwordx4 v[44:45], off
	v_lshl_add_u64 v[44:45], v[42:43], 0, s[24:25]
	v_readfirstlane_b32 s24, v47
	s_mov_b32 m0, s24
	s_mov_b64 s[24:25], 0x207000
	global_load_lds_dwordx4 v[44:45], off
	v_add_u32_e32 v44, 0x3000, v46
	v_lshl_add_u64 v[42:43], v[42:43], 0, s[24:25]
	v_readfirstlane_b32 s24, v44
	s_mov_b32 m0, s24
	s_mov_b64 s[24:25], 0x10a00040
	global_load_lds_dwordx4 v[42:43], off
	v_lshl_add_u64 v[42:43], v[34:35], 0, s[0:1]
	v_add_u32_e32 v47, 0x4000, v46
	v_lshl_add_u64 v[44:45], v[42:43], 0, s[24:25]
	v_readfirstlane_b32 s24, v47
	s_mov_b32 m0, s24
	s_mov_b64 s[24:25], 0x10a20040
	global_load_lds_dwordx4 v[44:45], off
	v_add_u32_e32 v44, 0x5000, v46
	v_lshl_add_u64 v[42:43], v[42:43], 0, s[24:25]
	v_readfirstlane_b32 s24, v44
	s_mov_b32 m0, s24
	s_nop 0
	global_load_lds_dwordx4 v[42:43], off
	s_cselect_b32 s24, 0, 0x6000
	v_or_b32_e32 v42, s24, v40
	v_add3_u32 v42, v42, v39, v38
	v_add_u32_e32 v43, s24, v41
	v_add3_u32 v74, v43, v39, v38
	ds_read_b128 v[42:45], v42 offset:16384
	ds_read_b128 v[46:49], v74
	ds_read_b128 v[50:53], v74 offset:1024
	ds_read_b128 v[54:57], v74 offset:2048
	ds_read_b128 v[58:61], v74 offset:3072
	ds_read_b128 v[62:65], v74 offset:4096
	ds_read_b128 v[66:69], v74 offset:5120
	ds_read_b128 v[70:73], v74 offset:6144
	ds_read_b128 v[74:77], v74 offset:7168
	s_setprio 1
	s_waitcnt lgkmcnt(0)
	v_mfma_f32_16x16x32_bf16 v[28:31], v[42:45], v[46:49], v[28:31]
	v_mfma_f32_16x16x32_bf16 v[24:27], v[42:45], v[50:53], v[24:27]
	v_mfma_f32_16x16x32_bf16 v[20:23], v[42:45], v[54:57], v[20:23]
	v_mfma_f32_16x16x32_bf16 v[16:19], v[42:45], v[58:61], v[16:19]
	v_mfma_f32_16x16x32_bf16 v[12:15], v[42:45], v[62:65], v[12:15]
	v_mfma_f32_16x16x32_bf16 v[8:11], v[42:45], v[66:69], v[8:11]
	v_mfma_f32_16x16x32_bf16 v[4:7], v[42:45], v[70:73], v[4:7]
	v_mfma_f32_16x16x32_bf16 v[0:3], v[42:45], v[74:77], v[0:3]
	s_setprio 0
	s_add_u32 s0, s0, 64
	s_addc_u32 s1, s1, 0
	s_add_u32 s100, s100, 0x204000
	s_addc_u32 s101, s101, 0
	s_add_i32 s76, s76, 1
	s_cmpk_eq_i32 s0, 0x7c0
	s_waitcnt vmcnt(0)
	s_barrier
	s_cbranch_scc0 .LBB0_257
	v_add3_u32 v32, v40, v39, v38
	v_add3_u32 v37, v41, v39, v38
	ds_read_b128 v[32:35], v32 offset:40960
	ds_read_b128 v[38:41], v37 offset:24576
	ds_read_b128 v[42:45], v37 offset:25600
	ds_read_b128 v[46:49], v37 offset:26624
	ds_read_b128 v[50:53], v37 offset:27648
	ds_read_b128 v[54:57], v37 offset:28672
	ds_read_b128 v[58:61], v37 offset:29696
	ds_read_b128 v[62:65], v37 offset:30720
	ds_read_b128 v[66:69], v37 offset:31744
	s_setprio 1
	s_waitcnt lgkmcnt(7)
	v_mfma_f32_16x16x32_bf16 v[28:31], v[32:35], v[38:41], v[28:31]
	s_waitcnt lgkmcnt(6)
	v_mfma_f32_16x16x32_bf16 v[24:27], v[32:35], v[42:45], v[24:27]
	s_waitcnt lgkmcnt(5)
	v_mfma_f32_16x16x32_bf16 v[20:23], v[32:35], v[46:49], v[20:23]
	s_waitcnt lgkmcnt(4)
	v_mfma_f32_16x16x32_bf16 v[16:19], v[32:35], v[50:53], v[16:19]
	s_waitcnt lgkmcnt(3)
	v_mfma_f32_16x16x32_bf16 v[12:15], v[32:35], v[54:57], v[12:15]
	s_waitcnt lgkmcnt(2)
	v_mfma_f32_16x16x32_bf16 v[8:11], v[32:35], v[58:61], v[8:11]
	s_waitcnt lgkmcnt(1)
	v_mfma_f32_16x16x32_bf16 v[4:7], v[32:35], v[62:65], v[4:7]
	s_waitcnt lgkmcnt(0)
	v_mfma_f32_16x16x32_bf16 v[0:3], v[32:35], v[66:69], v[0:3]
	s_setprio 0
	v_and_b32_e32 v32, 64, v36
	v_cmp_eq_u32_e32 vcc, 0, v32
	s_barrier
	s_and_saveexec_b64 s[0:1], vcc
	s_cbranch_execz .LBB0_260
	v_and_b32_e32 v32, 0xffffff80, v36
	v_add_u32_e32 v32, s33, v32
	v_and_or_b32 v32, v36, 15, v32
	v_and_b32_e32 v128, 48, v36
	v_ashrrev_i32_e32 v33, 31, v32
	v_lshl_add_u64 v[34:35], s[6:7], 0, v[128:129]
	v_lshlrev_b64 v[36:37], 6, v[32:33]
	v_lshl_add_u64 v[36:37], v[34:35], 0, v[36:37]
	global_store_dwordx4 v[36:37], v[28:31], off
	s_nop 1
	v_or_b32_e32 v28, 16, v32
	v_ashrrev_i32_e32 v29, 31, v28
	v_lshlrev_b64 v[28:29], 6, v[28:29]
	v_lshl_add_u64 v[28:29], v[34:35], 0, v[28:29]
	global_store_dwordx4 v[28:29], v[24:27], off
	s_nop 1
	v_or_b32_e32 v24, 32, v32
	v_ashrrev_i32_e32 v25, 31, v24
	v_lshlrev_b64 v[24:25], 6, v[24:25]
	v_lshl_add_u64 v[24:25], v[34:35], 0, v[24:25]
	global_store_dwordx4 v[24:25], v[20:23], off
	s_nop 1
	v_or_b32_e32 v20, 48, v32
	v_ashrrev_i32_e32 v21, 31, v20
	v_lshlrev_b64 v[20:21], 6, v[20:21]
	v_lshl_add_u64 v[20:21], v[34:35], 0, v[20:21]
	global_store_dwordx4 v[20:21], v[16:19], off
	s_nop 1
	v_or_b32_e32 v16, 64, v32
	v_ashrrev_i32_e32 v17, 31, v16
	v_lshlrev_b64 v[16:17], 6, v[16:17]
	v_lshl_add_u64 v[16:17], v[34:35], 0, v[16:17]
	global_store_dwordx4 v[16:17], v[12:15], off
	s_nop 1
	v_or_b32_e32 v12, 0x50, v32
	v_ashrrev_i32_e32 v13, 31, v12
	v_lshlrev_b64 v[12:13], 6, v[12:13]
	v_lshl_add_u64 v[12:13], v[34:35], 0, v[12:13]
	global_store_dwordx4 v[12:13], v[8:11], off
	s_nop 1
	v_or_b32_e32 v8, 0x60, v32
	v_ashrrev_i32_e32 v9, 31, v8
	v_lshlrev_b64 v[8:9], 6, v[8:9]
	v_lshl_add_u64 v[8:9], v[34:35], 0, v[8:9]
	global_store_dwordx4 v[8:9], v[4:7], off
	s_nop 1
	v_or_b32_e32 v4, 0x70, v32
	v_ashrrev_i32_e32 v5, 31, v4
	v_lshlrev_b64 v[4:5], 6, v[4:5]
	v_lshl_add_u64 v[4:5], v[34:35], 0, v[4:5]
	global_store_dwordx4 v[4:5], v[0:3], off

.LBB0_261:
	s_and_b64 vcc, exec, s[0:1]
	s_cbranch_vccz .LBB0_254
	v_mov_b32_e32 v141, v181
	v_mov_b32_e32 v10, v181
	s_lshl_b32 s76, s96, 7
	s_waitcnt vmcnt(0)
	v_ashrrev_i32_e32 v0, 2, v10
	v_ashrrev_i32_e32 v1, 31, v0
	v_add_u32_e32 v8, s76, v0
	v_lshlrev_b64 v[2:3], 6, v[0:1]
	v_lshlrev_b32_e32 v1, 3, v10
	v_ashrrev_i32_e32 v9, 31, v8
	v_bitop3_b32 v6, v1, 24, v10 bitop3:0x48
	v_lshlrev_b64 v[8:9], 11, v[8:9]
	v_lshl_add_u64 v[4:5], s[50:51], 0, v[2:3]
	v_lshlrev_b32_e32 v128, 1, v6
	v_lshl_add_u64 v[8:9], s[4:5], 0, v[8:9]
	v_lshl_add_u64 v[4:5], v[4:5], 0, v[128:129]
	v_lshl_add_u64 v[8:9], v[8:9], 0, v[128:129]
	v_lshlrev_b32_e32 v128, 4, v10
	v_add_u32_e32 v12, 0x1000, v128
	v_readfirstlane_b32 s0, v128
	v_lshl_add_u64 v[6:7], v[4:5], 0, s[10:11]
	s_mov_b32 m0, s0
	v_readfirstlane_b32 s0, v12
	v_add_u32_e32 v12, 0x2000, v128
	s_barrier
	global_load_lds_dwordx4 v[6:7], off
	v_lshl_add_u64 v[6:7], v[4:5], 0, s[12:13]
	s_mov_b32 m0, s0
	v_readfirstlane_b32 s0, v12
	global_load_lds_dwordx4 v[6:7], off
	v_lshl_add_u64 v[6:7], v[4:5], 0, s[14:15]
	s_mov_b32 m0, s0
	v_lshl_add_u64 v[4:5], v[4:5], 0, s[16:17]
	global_load_lds_dwordx4 v[6:7], off
	v_add_u32_e32 v6, 0x3000, v128
	v_xor_b32_e32 v11, v1, v10
	v_readfirstlane_b32 s0, v6
	s_mov_b32 m0, s0
	v_add_u32_e32 v6, 0x5000, v128
	global_load_lds_dwordx4 v[4:5], off
	v_add_u32_e32 v4, 0x4000, v128
	v_bitop3_b32 v134, v1, 48, v10 bitop3:0x48
	v_readfirstlane_b32 s0, v4
	s_mov_b32 m0, s0
	v_readfirstlane_b32 s0, v6
	global_load_lds_dwordx4 v[8:9], off
	v_lshl_add_u64 v[4:5], v[8:9], 0, s[8:9]
	s_mov_b32 m0, s0
	v_lshlrev_b32_e32 v1, 6, v10
	global_load_lds_dwordx4 v[4:5], off
	v_and_b32_e32 v137, 0x1000, v1
	v_and_b32_e32 v135, 0x3c0, v1
	v_and_b32_e32 v136, 0xffffe000, v1
	v_lshlrev_b32_e32 v1, 1, v11
	v_add_u32_e32 v0, s85, v0
	v_and_b32_e32 v4, 48, v1
	v_ashrrev_i32_e32 v1, 31, v0
	v_lshlrev_b64 v[0:1], 11, v[0:1]
	v_or_b32_e32 v0, v0, v4
	v_or_b32_e32 v2, v2, v4
	v_lshl_add_u64 v[132:133], s[20:21], 0, v[0:1]
	v_mov_b32_e32 v0, 0
	s_mov_b32 s77, 1
	v_lshl_add_u64 v[130:131], s[50:51], 0, v[2:3]
	s_mov_b64 s[0:1], 0
	s_mov_b64 s[100:101], 0
	v_mov_b32_e32 v1, v0
	v_mov_b32_e32 v2, v0
	v_mov_b32_e32 v3, v0
	v_mov_b32_e32 v4, v0
	v_mov_b32_e32 v5, v0
	v_mov_b32_e32 v6, v0
	v_mov_b32_e32 v7, v0
	v_mov_b32_e32 v8, v0
	v_mov_b32_e32 v9, v0
	v_mov_b32_e32 v10, v0
	v_mov_b32_e32 v11, v0
	v_mov_b32_e32 v12, v0
	v_mov_b32_e32 v13, v0
	v_mov_b32_e32 v14, v0
	v_mov_b32_e32 v15, v0
	v_mov_b32_e32 v16, v0
	v_mov_b32_e32 v17, v0
	v_mov_b32_e32 v18, v0
	v_mov_b32_e32 v19, v0
	v_mov_b32_e32 v20, v0
	v_mov_b32_e32 v21, v0
	v_mov_b32_e32 v22, v0
	v_mov_b32_e32 v23, v0
	v_mov_b32_e32 v24, v0
	v_mov_b32_e32 v25, v0
	v_mov_b32_e32 v26, v0
	v_mov_b32_e32 v27, v0
	v_mov_b32_e32 v28, v0
	v_mov_b32_e32 v29, v0
	v_mov_b32_e32 v30, v0
	v_mov_b32_e32 v31, v0
	v_mov_b32_e32 v32, v0
	v_mov_b32_e32 v33, v0
	v_mov_b32_e32 v34, v0
	v_mov_b32_e32 v35, v0
	v_mov_b32_e32 v36, v0
	v_mov_b32_e32 v37, v0
	v_mov_b32_e32 v38, v0
	v_mov_b32_e32 v39, v0
	v_mov_b32_e32 v40, v0
	v_mov_b32_e32 v41, v0
	v_mov_b32_e32 v42, v0
	v_mov_b32_e32 v43, v0
	v_mov_b32_e32 v44, v0
	v_mov_b32_e32 v45, v0
	v_mov_b32_e32 v46, v0
	v_mov_b32_e32 v47, v0
	v_mov_b32_e32 v48, v0
	v_mov_b32_e32 v49, v0
	v_mov_b32_e32 v50, v0
	v_mov_b32_e32 v51, v0
	v_mov_b32_e32 v52, v0
	v_mov_b32_e32 v53, v0
	v_mov_b32_e32 v54, v0
	v_mov_b32_e32 v55, v0
	v_mov_b32_e32 v56, v0
	v_mov_b32_e32 v57, v0
	v_mov_b32_e32 v58, v0
	v_mov_b32_e32 v59, v0
	v_mov_b32_e32 v64, v0
	v_mov_b32_e32 v65, v0
	v_mov_b32_e32 v66, v0
	v_mov_b32_e32 v67, v0
	v_mov_b32_e32 v60, v0
	v_mov_b32_e32 v61, v0
	v_mov_b32_e32 v62, v0
	v_mov_b32_e32 v63, v0
	v_mov_b32_e32 v68, v0
	v_mov_b32_e32 v69, v0
	v_mov_b32_e32 v70, v0
	v_mov_b32_e32 v71, v0
	v_mov_b32_e32 v72, v0
	v_mov_b32_e32 v73, v0
	v_mov_b32_e32 v74, v0
	v_mov_b32_e32 v75, v0
	v_mov_b32_e32 v76, v0
	v_mov_b32_e32 v77, v0
	v_mov_b32_e32 v78, v0
	v_mov_b32_e32 v79, v0
	v_mov_b32_e32 v80, v0
	v_mov_b32_e32 v81, v0
	v_mov_b32_e32 v82, v0
	v_mov_b32_e32 v83, v0
	v_mov_b32_e32 v84, v0
	v_mov_b32_e32 v85, v0
	v_mov_b32_e32 v86, v0
	v_mov_b32_e32 v87, v0
	v_mov_b32_e32 v88, v0
	v_mov_b32_e32 v89, v0
	v_mov_b32_e32 v90, v0
	v_mov_b32_e32 v91, v0
	v_mov_b32_e32 v92, v0
	v_mov_b32_e32 v93, v0
	v_mov_b32_e32 v94, v0
	v_mov_b32_e32 v95, v0
	v_mov_b32_e32 v96, v0
	v_mov_b32_e32 v97, v0
	v_mov_b32_e32 v98, v0
	v_mov_b32_e32 v99, v0
	v_mov_b32_e32 v100, v0
	v_mov_b32_e32 v101, v0
	v_mov_b32_e32 v102, v0
	v_mov_b32_e32 v103, v0
	v_mov_b32_e32 v104, v0
	v_mov_b32_e32 v105, v0
	v_mov_b32_e32 v106, v0
	v_mov_b32_e32 v107, v0
	v_mov_b32_e32 v108, v0
	v_mov_b32_e32 v109, v0
	v_mov_b32_e32 v110, v0
	v_mov_b32_e32 v111, v0
	v_mov_b32_e32 v112, v0
	v_mov_b32_e32 v113, v0
	v_mov_b32_e32 v114, v0
	v_mov_b32_e32 v115, v0
	v_mov_b32_e32 v116, v0
	v_mov_b32_e32 v117, v0
	v_mov_b32_e32 v118, v0
	v_mov_b32_e32 v119, v0
	v_mov_b32_e32 v120, v0
	v_mov_b32_e32 v121, v0
	v_mov_b32_e32 v122, v0
	v_mov_b32_e32 v123, v0
	v_mov_b32_e32 v124, v0
	v_mov_b32_e32 v125, v0
	v_mov_b32_e32 v126, v0
	v_mov_b32_e32 v127, v0
	s_waitcnt vmcnt(0) lgkmcnt(0)
	s_barrier
.LBB0_263:
	s_bitcmp1_b32 s77, 0
	s_cselect_b32 s24, 0x6000, 0
	v_add_u32_e32 v144, s24, v128
	v_lshl_add_u64 v[138:139], v[130:131], 0, s[100:101]
	v_readfirstlane_b32 s24, v144
	v_add_u32_e32 v145, 0x1000, v144
	v_lshl_add_u64 v[142:143], v[138:139], 0, s[34:35]
	s_mov_b32 m0, s24
	v_readfirstlane_b32 s24, v145
	v_add_u32_e32 v145, 0x2000, v144
	global_load_lds_dwordx4 v[142:143], off
	v_lshl_add_u64 v[142:143], v[138:139], 0, s[46:47]
	s_mov_b32 m0, s24
	v_readfirstlane_b32 s24, v145
	global_load_lds_dwordx4 v[142:143], off
	v_lshl_add_u64 v[142:143], v[138:139], 0, s[62:63]
	s_mov_b32 m0, s24
	v_lshl_add_u64 v[138:139], v[138:139], 0, s[64:65]
	global_load_lds_dwordx4 v[142:143], off
	v_add_u32_e32 v142, 0x3000, v144
	v_add_u32_e32 v145, 0x4000, v144
	v_readfirstlane_b32 s24, v142
	s_mov_b32 m0, s24
	v_readfirstlane_b32 s24, v145
	global_load_lds_dwordx4 v[138:139], off
	v_lshl_add_u64 v[138:139], v[132:133], 0, s[0:1]
	v_lshl_add_u64 v[142:143], v[138:139], 0, s[68:69]
	s_mov_b32 m0, s24
	v_lshl_add_u64 v[138:139], v[138:139], 0, s[70:71]
	global_load_lds_dwordx4 v[142:143], off
	v_add_u32_e32 v142, 0x5000, v144
	s_nop 0
	v_readfirstlane_b32 s24, v142
	s_mov_b32 m0, s24
	s_nop 0
	global_load_lds_dwordx4 v[138:139], off
	s_cselect_b32 s24, 0, 0x6000
	v_or_b32_e32 v138, s24, v137
	v_add3_u32 v138, v138, v135, v134
	ds_read_b128 v[142:145], v138 offset:16384
	ds_read_b128 v[146:149], v138 offset:17408
	ds_read_b128 v[150:153], v138 offset:18432
	ds_read_b128 v[154:157], v138 offset:19456
	v_add_u32_e32 v138, s24, v136
	v_add3_u32 v138, v138, v135, v134
	ds_read_b128 v[158:161], v138
	ds_read_b128 v[162:165], v138 offset:1024
	ds_read_b128 v[166:169], v138 offset:2048
	ds_read_b128 v[170:173], v138 offset:3072
	ds_read_b128 v[174:177], v138 offset:4096
	ds_read_b128 v[184:187], v138 offset:5120
	ds_read_b128 v[188:191], v138 offset:6144
	ds_read_b128 v[192:195], v138 offset:7168
	s_setprio 1
	s_waitcnt lgkmcnt(0)
	v_mfma_f32_16x16x32_bf16 v[124:127], v[142:145], v[158:161], v[124:127]
	v_mfma_f32_16x16x32_bf16 v[120:123], v[146:149], v[158:161], v[120:123]
	v_mfma_f32_16x16x32_bf16 v[116:119], v[150:153], v[158:161], v[116:119]
	v_mfma_f32_16x16x32_bf16 v[112:115], v[154:157], v[158:161], v[112:115]
	v_mfma_f32_16x16x32_bf16 v[108:111], v[142:145], v[162:165], v[108:111]
	v_mfma_f32_16x16x32_bf16 v[104:107], v[146:149], v[162:165], v[104:107]
	v_mfma_f32_16x16x32_bf16 v[100:103], v[150:153], v[162:165], v[100:103]
	v_mfma_f32_16x16x32_bf16 v[96:99], v[154:157], v[162:165], v[96:99]
	v_mfma_f32_16x16x32_bf16 v[92:95], v[142:145], v[166:169], v[92:95]
	v_mfma_f32_16x16x32_bf16 v[88:91], v[146:149], v[166:169], v[88:91]
	v_mfma_f32_16x16x32_bf16 v[84:87], v[150:153], v[166:169], v[84:87]
	v_mfma_f32_16x16x32_bf16 v[80:83], v[154:157], v[166:169], v[80:83]
	v_mfma_f32_16x16x32_bf16 v[76:79], v[142:145], v[170:173], v[76:79]
	v_mfma_f32_16x16x32_bf16 v[72:75], v[146:149], v[170:173], v[72:75]
	v_mfma_f32_16x16x32_bf16 v[68:71], v[150:153], v[170:173], v[68:71]
	v_mfma_f32_16x16x32_bf16 v[60:63], v[154:157], v[170:173], v[60:63]
	v_mfma_f32_16x16x32_bf16 v[64:67], v[142:145], v[174:177], v[64:67]
	v_mfma_f32_16x16x32_bf16 v[56:59], v[146:149], v[174:177], v[56:59]
	v_mfma_f32_16x16x32_bf16 v[52:55], v[150:153], v[174:177], v[52:55]
	v_mfma_f32_16x16x32_bf16 v[48:51], v[154:157], v[174:177], v[48:51]
	v_mfma_f32_16x16x32_bf16 v[44:47], v[142:145], v[184:187], v[44:47]
	v_mfma_f32_16x16x32_bf16 v[40:43], v[146:149], v[184:187], v[40:43]
	v_mfma_f32_16x16x32_bf16 v[36:39], v[150:153], v[184:187], v[36:39]
	v_mfma_f32_16x16x32_bf16 v[32:35], v[154:157], v[184:187], v[32:35]
	v_mfma_f32_16x16x32_bf16 v[28:31], v[142:145], v[188:191], v[28:31]
	v_mfma_f32_16x16x32_bf16 v[24:27], v[146:149], v[188:191], v[24:27]
	v_mfma_f32_16x16x32_bf16 v[20:23], v[150:153], v[188:191], v[20:23]
	v_mfma_f32_16x16x32_bf16 v[16:19], v[154:157], v[188:191], v[16:19]
	v_mfma_f32_16x16x32_bf16 v[12:15], v[142:145], v[192:195], v[12:15]
	v_mfma_f32_16x16x32_bf16 v[8:11], v[146:149], v[192:195], v[8:11]
	v_mfma_f32_16x16x32_bf16 v[4:7], v[150:153], v[192:195], v[4:7]
	v_mfma_f32_16x16x32_bf16 v[0:3], v[154:157], v[192:195], v[0:3]
	s_setprio 0
	s_add_u32 s0, s0, 64
	s_addc_u32 s1, s1, 0
	s_add_u32 s100, s100, 0x204000
	s_addc_u32 s101, s101, 0
	s_add_i32 s77, s77, 1
	s_cmpk_eq_i32 s0, 0x7c0
	s_waitcnt vmcnt(0)
	s_barrier
	s_cbranch_scc0 .LBB0_263
	v_bfe_u32 v144, v141, 6, 1
	v_and_b32_e32 v143, 15, v141
	v_bfe_u32 v145, v141, 4, 2
	v_add3_u32 v128, v137, v135, v134
	ds_read_b128 v[130:133], v128 offset:40960
	ds_read_b128 v[146:149], v128 offset:41984
	ds_read_b128 v[150:153], v128 offset:43008
	ds_read_b128 v[154:157], v128 offset:44032
	v_add3_u32 v128, v136, v135, v134
	ds_read_b128 v[134:137], v128 offset:24576
	ds_read_b128 v[158:161], v128 offset:25600
	ds_read_b128 v[162:165], v128 offset:26624
	ds_read_b128 v[166:169], v128 offset:27648
	ds_read_b128 v[170:173], v128 offset:28672
	ds_read_b128 v[174:177], v128 offset:29696
	ds_read_b128 v[184:187], v128 offset:30720
	ds_read_b128 v[188:191], v128 offset:31744
	s_setprio 1
	s_waitcnt lgkmcnt(7)
	v_mfma_f32_16x16x32_bf16 v[124:127], v[130:133], v[134:137], v[124:127]
	v_mfma_f32_16x16x32_bf16 v[120:123], v[146:149], v[134:137], v[120:123]
	v_mfma_f32_16x16x32_bf16 v[116:119], v[150:153], v[134:137], v[116:119]
	v_mfma_f32_16x16x32_bf16 v[112:115], v[154:157], v[134:137], v[112:115]
	s_waitcnt lgkmcnt(6)
	v_mfma_f32_16x16x32_bf16 v[108:111], v[130:133], v[158:161], v[108:111]
	v_mfma_f32_16x16x32_bf16 v[104:107], v[146:149], v[158:161], v[104:107]
	v_mfma_f32_16x16x32_bf16 v[100:103], v[150:153], v[158:161], v[100:103]
	v_mfma_f32_16x16x32_bf16 v[96:99], v[154:157], v[158:161], v[96:99]
	s_waitcnt lgkmcnt(5)
	v_mfma_f32_16x16x32_bf16 v[92:95], v[130:133], v[162:165], v[92:95]
	v_mfma_f32_16x16x32_bf16 v[88:91], v[146:149], v[162:165], v[88:91]
	v_mfma_f32_16x16x32_bf16 v[84:87], v[150:153], v[162:165], v[84:87]
	v_mfma_f32_16x16x32_bf16 v[80:83], v[154:157], v[162:165], v[80:83]
	s_waitcnt lgkmcnt(4)
	v_mfma_f32_16x16x32_bf16 v[76:79], v[130:133], v[166:169], v[76:79]
	v_mfma_f32_16x16x32_bf16 v[72:75], v[146:149], v[166:169], v[72:75]
	v_mfma_f32_16x16x32_bf16 v[68:71], v[150:153], v[166:169], v[68:71]
	v_mfma_f32_16x16x32_bf16 v[60:63], v[154:157], v[166:169], v[60:63]
	s_waitcnt lgkmcnt(3)
	v_mfma_f32_16x16x32_bf16 v[64:67], v[130:133], v[170:173], v[64:67]
	v_mfma_f32_16x16x32_bf16 v[56:59], v[146:149], v[170:173], v[56:59]
	v_mfma_f32_16x16x32_bf16 v[52:55], v[150:153], v[170:173], v[52:55]
	v_mfma_f32_16x16x32_bf16 v[48:51], v[154:157], v[170:173], v[48:51]
	s_waitcnt lgkmcnt(2)
	v_mfma_f32_16x16x32_bf16 v[44:47], v[130:133], v[174:177], v[44:47]
	v_mfma_f32_16x16x32_bf16 v[40:43], v[146:149], v[174:177], v[40:43]
	v_mfma_f32_16x16x32_bf16 v[36:39], v[150:153], v[174:177], v[36:39]
	v_mfma_f32_16x16x32_bf16 v[32:35], v[154:157], v[174:177], v[32:35]
	s_waitcnt lgkmcnt(1)
	v_mfma_f32_16x16x32_bf16 v[28:31], v[130:133], v[184:187], v[28:31]
	v_mfma_f32_16x16x32_bf16 v[24:27], v[146:149], v[184:187], v[24:27]
	v_mfma_f32_16x16x32_bf16 v[20:23], v[150:153], v[184:187], v[20:23]
	v_mfma_f32_16x16x32_bf16 v[16:19], v[154:157], v[184:187], v[16:19]
	s_waitcnt lgkmcnt(0)
	v_mfma_f32_16x16x32_bf16 v[12:15], v[130:133], v[188:191], v[12:15]
	v_mfma_f32_16x16x32_bf16 v[8:11], v[146:149], v[188:191], v[8:11]
	v_mfma_f32_16x16x32_bf16 v[4:7], v[150:153], v[188:191], v[4:7]
	v_mfma_f32_16x16x32_bf16 v[0:3], v[154:157], v[188:191], v[0:3]
	s_setprio 0
	s_cmp_lt_i32 s96, 12
	v_and_b32_e32 v142, 0xffffff80, v141
	s_barrier
	s_cbranch_scc0 .LBB0_364
	v_lshlrev_b32_e32 v128, 6, v144
	v_lshlrev_b32_e32 v130, 2, v145
	v_lshrrev_b32_e32 v131, 4, v142
	v_add_u32_e32 v147, 0x8000, v142
	v_or3_b32 v130, v128, v130, s76
	v_subrev_co_u32_e32 v128, vcc, 13, v143
	v_lshl_add_u32 v148, v131, 1, v131
	v_or_b32_e32 v146, v147, v143
	v_add_u32_e32 v131, v148, v128
	v_mov_b64_e32 v[132:133], s[50:51]
	s_xor_b64 s[78:79], vcc, -1
	v_cmp_lt_i32_e32 vcc, s87, v146
	v_mad_u64_u32 v[132:133], s[0:1], v131, s90, v[132:133]
	v_lshl_add_u64 v[138:139], v[132:133], 0, s[72:73]
	s_and_b64 s[0:1], vcc, s[78:79]
	v_ashrrev_i32_e32 v131, 31, v130
	s_and_saveexec_b64 s[80:81], s[0:1]
	s_cbranch_execnz .LBB0_368
	s_or_b64 exec, exec, s[80:81]
	s_and_saveexec_b64 s[80:81], s[0:1]
	s_cbranch_execnz .LBB0_369

	.amdhsa_kernel _Z14fwd_megakernel6Params
		.amdhsa_group_segment_fixed_size 73728
		.amdhsa_private_segment_fixed_size 0
		.amdhsa_kernarg_size 392
		.amdhsa_user_sgpr_count 2
		.amdhsa_user_sgpr_dispatch_ptr 0
		.amdhsa_user_sgpr_queue_ptr 0
		.amdhsa_user_sgpr_kernarg_segment_ptr 1
		.amdhsa_user_sgpr_dispatch_id 0
		.amdhsa_user_sgpr_kernarg_preload_length 0
		.amdhsa_user_sgpr_kernarg_preload_offset 0
		.amdhsa_user_sgpr_private_segment_size 0
		.amdhsa_uses_dynamic_stack 0
		.amdhsa_enable_private_segment 0
		.amdhsa_system_sgpr_workgroup_id_x 1
		.amdhsa_system_sgpr_workgroup_id_y 0
		.amdhsa_system_sgpr_workgroup_id_z 0
		.amdhsa_system_sgpr_workgroup_info 0
		.amdhsa_system_vgpr_workitem_id 2
		.amdhsa_next_free_vgpr 245
		.amdhsa_next_free_sgpr 102
		.amdhsa_accum_offset 248
		.amdhsa_reserve_vcc 1
		.amdhsa_float_round_mode_32 0
		.amdhsa_float_round_mode_16_64 0
		.amdhsa_float_denorm_mode_32 3
		.amdhsa_float_denorm_mode_16_64 3
		.amdhsa_dx10_clamp 1
		.amdhsa_ieee_mode 1
		.amdhsa_fp16_overflow 0
		.amdhsa_tg_split 0
		.amdhsa_exception_fp_ieee_invalid_op 0
		.amdhsa_exception_fp_denorm_src 0
		.amdhsa_exception_fp_ieee_div_zero 0
		.amdhsa_exception_fp_ieee_overflow 0
		.amdhsa_exception_fp_ieee_underflow 0
		.amdhsa_exception_fp_ieee_inexact 0
		.amdhsa_exception_int_div_zero 0
	.end_amdhsa_kernel

amdhsa.kernels:
  - .agpr_count:     0
    .args:
      - .offset:         0
        .size:           136
        .value_kind:     by_value
      - .offset:         136
        .size:           4
        .value_kind:     hidden_block_count_x
      - .offset:         140
        .size:           4
        .value_kind:     hidden_block_count_y
      - .offset:         144
        .size:           4
        .value_kind:     hidden_block_count_z
      - .offset:         148
        .size:           2
        .value_kind:     hidden_group_size_x
      - .offset:         150
        .size:           2
        .value_kind:     hidden_group_size_y
      - .offset:         152
        .size:           2
        .value_kind:     hidden_group_size_z
      - .offset:         154
        .size:           2
        .value_kind:     hidden_remainder_x
      - .offset:         156
        .size:           2
        .value_kind:     hidden_remainder_y
      - .offset:         158
        .size:           2
        .value_kind:     hidden_remainder_z
      - .offset:         176
        .size:           8
        .value_kind:     hidden_global_offset_x
      - .offset:         184
        .size:           8
        .value_kind:     hidden_global_offset_y
      - .offset:         192
        .size:           8
        .value_kind:     hidden_global_offset_z
      - .offset:         200
        .size:           2
        .value_kind:     hidden_grid_dims
      - .offset:         224
        .size:           8
        .value_kind:     hidden_multigrid_sync_arg
    .group_segment_fixed_size: 73728
    .kernarg_segment_align: 8
    .kernarg_segment_size: 392
    .language:       OpenCL C
    .language_version:
      - 2
      - 0
    .max_flat_workgroup_size: 256
    .name:           _Z14fwd_megakernel6Params
    .private_segment_fixed_size: 0
    .sgpr_count:     108
    .sgpr_spill_count: 6
    .symbol:         _Z14fwd_megakernel6Params.kd
    .uniform_work_group_size: 1
    .uses_dynamic_stack: false
    .vgpr_count:     245
    .vgpr_spill_count: 0
    .wavefront_size: 64
